# nt hint also on the once-read gate-logit loads of the P5 epilogue (on top of nt output stores for P2 and P8)
# baseline (speedup 1.0000x reference)
.LBB0_137:
	v_mov_b32_e32 v148, v211
	s_nop 0
	v_ashrrev_i32_e32 v146, 3, v148
	v_mad_i64_i32 v[0:1], s[20:21], v146, s38, 0
	v_lshlrev_b32_e32 v2, 4, v148
	v_and_b32_e32 v145, 0x70, v2
	s_add_u32 s20, s2, s15
	v_ashrrev_i32_e32 v147, 31, v146
	v_or_b32_e32 v0, v0, v145
	s_addc_u32 s21, s3, s13
	v_lshl_add_u64 v[12:13], s[20:21], 0, v[0:1]
	v_lshlrev_b64 v[0:1], 10, v[146:147]
	s_add_u32 s20, s2, s8
	v_or_b32_e32 v0, v0, v145
	s_addc_u32 s21, s3, s9
	v_lshl_add_u64 v[28:29], s[20:21], 0, v[0:1]
	s_mov_b32 s20, 0x28600000
	v_add_co_u32_e32 v128, vcc, s20, v12
	s_mov_b32 s20, 0x28618000
	s_nop 0
	v_addc_co_u32_e32 v129, vcc, 0, v13, vcc
	v_add_co_u32_e32 v130, vcc, s20, v12
	s_mov_b32 s20, 0x28630000
	s_nop 0
	v_addc_co_u32_e32 v131, vcc, 0, v13, vcc
	v_add_co_u32_e32 v132, vcc, s20, v12
	s_mov_b32 s20, 0x28648000
	s_nop 0
	v_addc_co_u32_e32 v133, vcc, 0, v13, vcc
	v_add_co_u32_e32 v134, vcc, s20, v12
	s_mov_b32 s20, 0x33c00000
	s_nop 0
	v_addc_co_u32_e32 v135, vcc, 0, v13, vcc
	global_load_dwordx4 v[0:3], v[128:129], off
	global_load_dwordx4 v[4:7], v[130:131], off
	v_add_co_u32_e32 v136, vcc, s20, v28
	s_mov_b32 s20, 0x33c08000
	s_nop 0
	v_addc_co_u32_e32 v137, vcc, 0, v29, vcc
	global_load_dwordx4 v[8:11], v[132:133], off
	global_load_dwordx4 v[12:15], v[134:135], off
	v_add_co_u32_e32 v138, vcc, s20, v28
	s_mov_b32 s20, 0x33c10000
	s_nop 0
	v_addc_co_u32_e32 v139, vcc, 0, v29, vcc
	global_load_dwordx4 v[16:19], v[136:137], off
	global_load_dwordx4 v[20:23], v[138:139], off
	v_add_co_u32_e32 v140, vcc, s20, v28
	s_mov_b32 s20, 0x33c18000
	s_nop 0
	v_addc_co_u32_e32 v141, vcc, 0, v29, vcc
	global_load_dwordx4 v[24:27], v[140:141], off
	v_add_co_u32_e32 v142, vcc, s20, v28
	v_mul_u32_u24_e32 v146, 0xa0, v146
	s_nop 0
	v_addc_co_u32_e32 v143, vcc, 0, v29, vcc
	global_load_dwordx4 v[28:31], v[142:143], off
	global_load_dwordx4 v[56:59], v[128:129], off offset:128
	global_load_dwordx4 v[60:63], v[130:131], off offset:128
	global_load_dwordx4 v[44:47], v[132:133], off offset:128
	global_load_dwordx4 v[48:51], v[134:135], off offset:128
	global_load_dwordx4 v[52:55], v[136:137], off offset:128
	global_load_dwordx4 v[32:35], v[138:139], off offset:128
	global_load_dwordx4 v[36:39], v[140:141], off offset:128
	global_load_dwordx4 v[40:43], v[142:143], off offset:128
	v_add3_u32 v145, 0, v146, v145
	s_barrier
	s_add_u32 s20, s17, s6
	s_addc_u32 s21, s18, s7
	s_waitcnt vmcnt(15)
	ds_write_b128 v145, v[0:3]
	s_waitcnt vmcnt(14)
	ds_write_b128 v145, v[4:7] offset:5120
	s_waitcnt vmcnt(13)
	ds_write_b128 v145, v[8:11] offset:10240
	s_waitcnt vmcnt(12)
	ds_write_b128 v145, v[12:15] offset:15360
	s_waitcnt vmcnt(11)
	ds_write_b128 v145, v[16:19] offset:20480
	s_waitcnt vmcnt(10)
	ds_write_b128 v145, v[20:23] offset:25600
	s_waitcnt vmcnt(9)
	ds_write_b128 v145, v[24:27] offset:30720
	s_waitcnt vmcnt(8)
	ds_write_b128 v145, v[28:31] offset:35840
	v_and_b32_e32 v0, 15, v148
	v_lshrrev_b32_e32 v1, 1, v148
	v_and_or_b32 v0, v1, s43, v0
	v_mul_u32_u24_e32 v0, 0xa0, v0
	v_and_b32_e32 v1, 48, v148
	v_add3_u32 v146, 0, v0, v1
	v_and_b32_e32 v0, 0x4f, v148
	v_mul_u32_u24_e32 v0, 0x50, v0
	v_lshlrev_b32_e32 v0, 1, v0
	s_waitcnt lgkmcnt(0)
	s_barrier
	v_add3_u32 v147, 0, v0, v1
	v_add_u32_e32 v147, 0x5000, v147
	global_load_dwordx4 v[0:3], v[128:129], off offset:256
	global_load_dwordx4 v[4:7], v[130:131], off offset:256
	global_load_dwordx4 v[8:11], v[132:133], off offset:256
	global_load_dwordx4 v[12:15], v[134:135], off offset:256
	global_load_dwordx4 v[16:19], v[136:137], off offset:256
	global_load_dwordx4 v[20:23], v[138:139], off offset:256
	global_load_dwordx4 v[24:27], v[140:141], off offset:256
	global_load_dwordx4 v[28:31], v[142:143], off offset:256
	ds_read_b128 v[150:153], v146
	ds_read_b128 v[154:157], v146 offset:2560
	ds_read_b128 v[158:161], v146 offset:5120
	ds_read_b128 v[162:165], v146 offset:7680
	ds_read_b128 v[166:169], v147
	ds_read_b128 v[170:173], v147 offset:2560
	ds_read_b128 v[174:177], v147 offset:5120
	ds_read_b128 v[178:181], v147 offset:7680
	v_add_u32_e32 v148, 0xf000, v145
	s_waitcnt lgkmcnt(3)
	v_mfma_f32_16x16x32_bf16 v[182:185], v[150:153], v[166:169], 0
	s_waitcnt lgkmcnt(2)
	v_mfma_f32_16x16x32_bf16 v[186:189], v[150:153], v[170:173], 0
	s_waitcnt lgkmcnt(1)
	v_mfma_f32_16x16x32_bf16 v[190:193], v[150:153], v[174:177], 0
	s_waitcnt lgkmcnt(0)
	v_mfma_f32_16x16x32_bf16 v[150:153], v[150:153], v[178:181], 0
	v_mfma_f32_16x16x32_bf16 v[194:197], v[154:157], v[166:169], 0
	v_mfma_f32_16x16x32_bf16 v[198:201], v[154:157], v[170:173], 0
	v_mfma_f32_16x16x32_bf16 v[202:205], v[154:157], v[174:177], 0
	v_mfma_f32_16x16x32_bf16 v[154:157], v[154:157], v[178:181], 0
	v_mfma_f32_16x16x32_bf16 v[212:215], v[158:161], v[166:169], 0
	v_mfma_f32_16x16x32_bf16 v[224:227], v[158:161], v[170:173], 0
	v_mfma_f32_16x16x32_bf16 v[228:231], v[158:161], v[174:177], 0
	v_mfma_f32_16x16x32_bf16 v[158:161], v[158:161], v[178:181], 0
	v_mfma_f32_16x16x32_bf16 v[166:169], v[162:165], v[166:169], 0
	v_mfma_f32_16x16x32_bf16 v[170:173], v[162:165], v[170:173], 0
	v_mfma_f32_16x16x32_bf16 v[174:177], v[162:165], v[174:177], 0
	v_mfma_f32_16x16x32_bf16 v[162:165], v[162:165], v[178:181], 0
	ds_read_b128 v[178:181], v146 offset:64
	ds_read_b128 v[232:235], v146 offset:2624
	ds_read_b128 v[236:239], v146 offset:5184
	ds_read_b128 v[240:243], v146 offset:7744
	ds_read_b128 v[244:247], v147 offset:64
	ds_read_b128 v[248:251], v147 offset:2624
	ds_read_b128 v[216:219], v147 offset:5184
	ds_read_b128 v[220:223], v147 offset:7744
	s_waitcnt vmcnt(15)
	ds_write_b128 v145, v[56:59] offset:40960
	s_waitcnt vmcnt(14)
	ds_write_b128 v145, v[60:63] offset:46080
	s_waitcnt vmcnt(13)
	ds_write_b128 v145, v[44:47] offset:51200
	s_waitcnt vmcnt(12)
	ds_write_b128 v145, v[48:51] offset:56320
	s_waitcnt vmcnt(11)
	ds_write_b128 v145, v[52:55] offset:61440
	s_waitcnt vmcnt(10)
	ds_write_b128 v148, v[32:35] offset:5120
	s_waitcnt vmcnt(9)
	ds_write_b128 v148, v[36:39] offset:10240
	s_waitcnt vmcnt(8)
	ds_write_b128 v148, v[40:43] offset:15360
	s_waitcnt lgkmcnt(0)
	s_barrier
	global_load_dwordx4 v[56:59], v[128:129], off offset:384
	global_load_dwordx4 v[60:63], v[130:131], off offset:384
	global_load_dwordx4 v[44:47], v[132:133], off offset:384
	global_load_dwordx4 v[48:51], v[134:135], off offset:384
	global_load_dwordx4 v[52:55], v[136:137], off offset:384
	global_load_dwordx4 v[32:35], v[138:139], off offset:384
	global_load_dwordx4 v[36:39], v[140:141], off offset:384
	global_load_dwordx4 v[40:43], v[142:143], off offset:384
	v_mfma_f32_16x16x32_bf16 v[182:185], v[178:181], v[244:247], v[182:185]
	v_mfma_f32_16x16x32_bf16 v[186:189], v[178:181], v[248:251], v[186:189]
	v_mfma_f32_16x16x32_bf16 v[190:193], v[178:181], v[216:219], v[190:193]
	v_mfma_f32_16x16x32_bf16 v[150:153], v[178:181], v[220:223], v[150:153]
	v_mfma_f32_16x16x32_bf16 v[178:181], v[232:235], v[244:247], v[194:197]
	v_mfma_f32_16x16x32_bf16 v[194:197], v[232:235], v[248:251], v[198:201]
	v_mfma_f32_16x16x32_bf16 v[198:201], v[232:235], v[216:219], v[202:205]
	v_mfma_f32_16x16x32_bf16 v[154:157], v[232:235], v[220:223], v[154:157]
	v_mfma_f32_16x16x32_bf16 v[202:205], v[236:239], v[244:247], v[212:215]
	v_mfma_f32_16x16x32_bf16 v[212:215], v[236:239], v[248:251], v[224:227]
	v_mfma_f32_16x16x32_bf16 v[224:227], v[236:239], v[216:219], v[228:231]
	v_mfma_f32_16x16x32_bf16 v[158:161], v[236:239], v[220:223], v[158:161]
	v_mfma_f32_16x16x32_bf16 v[166:169], v[240:243], v[244:247], v[166:169]
	v_mfma_f32_16x16x32_bf16 v[170:173], v[240:243], v[248:251], v[170:173]
	v_mfma_f32_16x16x32_bf16 v[174:177], v[240:243], v[216:219], v[174:177]
	v_mfma_f32_16x16x32_bf16 v[162:165], v[240:243], v[220:223], v[162:165]
	ds_read_b128 v[216:219], v146 offset:40960
	ds_read_b128 v[220:223], v146 offset:43520
	ds_read_b128 v[228:231], v146 offset:46080
	ds_read_b128 v[232:235], v146 offset:48640
	ds_read_b128 v[236:239], v147 offset:40960
	ds_read_b128 v[240:243], v147 offset:43520
	ds_read_b128 v[244:247], v147 offset:46080
	ds_read_b128 v[248:251], v147 offset:48640
	s_waitcnt lgkmcnt(3)
	v_mfma_f32_16x16x32_bf16 v[182:185], v[216:219], v[236:239], v[182:185]
	s_waitcnt lgkmcnt(2)
	v_mfma_f32_16x16x32_bf16 v[186:189], v[216:219], v[240:243], v[186:189]
	s_waitcnt lgkmcnt(1)
	v_mfma_f32_16x16x32_bf16 v[190:193], v[216:219], v[244:247], v[190:193]
	s_waitcnt lgkmcnt(0)
	v_mfma_f32_16x16x32_bf16 v[150:153], v[216:219], v[248:251], v[150:153]
	v_mfma_f32_16x16x32_bf16 v[178:181], v[220:223], v[236:239], v[178:181]
	v_mfma_f32_16x16x32_bf16 v[194:197], v[220:223], v[240:243], v[194:197]
	v_mfma_f32_16x16x32_bf16 v[198:201], v[220:223], v[244:247], v[198:201]
	v_mfma_f32_16x16x32_bf16 v[154:157], v[220:223], v[248:251], v[154:157]
	v_mfma_f32_16x16x32_bf16 v[202:205], v[228:231], v[236:239], v[202:205]
	v_mfma_f32_16x16x32_bf16 v[212:215], v[228:231], v[240:243], v[212:215]
	v_mfma_f32_16x16x32_bf16 v[216:219], v[228:231], v[244:247], v[224:227]
	v_mfma_f32_16x16x32_bf16 v[158:161], v[228:231], v[248:251], v[158:161]
	v_mfma_f32_16x16x32_bf16 v[166:169], v[232:235], v[236:239], v[166:169]
	v_mfma_f32_16x16x32_bf16 v[170:173], v[232:235], v[240:243], v[170:173]
	v_mfma_f32_16x16x32_bf16 v[174:177], v[232:235], v[244:247], v[174:177]
	v_mfma_f32_16x16x32_bf16 v[162:165], v[232:235], v[248:251], v[162:165]
	ds_read_b128 v[220:223], v146 offset:41024
	ds_read_b128 v[224:227], v146 offset:43584
	ds_read_b128 v[228:231], v146 offset:46144
	ds_read_b128 v[232:235], v146 offset:48704
	ds_read_b128 v[236:239], v147 offset:41024
	ds_read_b128 v[240:243], v147 offset:43584
	ds_read_b128 v[244:247], v147 offset:46144
	ds_read_b128 v[248:251], v147 offset:48704
	s_waitcnt vmcnt(15)
	ds_write_b128 v145, v[0:3]
	s_waitcnt vmcnt(14)
	ds_write_b128 v145, v[4:7] offset:5120
	s_waitcnt vmcnt(13)
	ds_write_b128 v145, v[8:11] offset:10240
	s_waitcnt vmcnt(12)
	ds_write_b128 v145, v[12:15] offset:15360
	s_waitcnt vmcnt(11)
	ds_write_b128 v145, v[16:19] offset:20480
	s_waitcnt vmcnt(10)
	ds_write_b128 v145, v[20:23] offset:25600
	s_waitcnt vmcnt(9)
	ds_write_b128 v145, v[24:27] offset:30720
	s_waitcnt vmcnt(8)
	ds_write_b128 v145, v[28:31] offset:35840
	s_waitcnt lgkmcnt(0)
	s_barrier
	global_load_dwordx4 v[0:3], v[128:129], off offset:512
	global_load_dwordx4 v[4:7], v[130:131], off offset:512
	global_load_dwordx4 v[8:11], v[132:133], off offset:512
	global_load_dwordx4 v[12:15], v[134:135], off offset:512
	global_load_dwordx4 v[16:19], v[136:137], off offset:512
	global_load_dwordx4 v[20:23], v[138:139], off offset:512
	global_load_dwordx4 v[24:27], v[140:141], off offset:512
	global_load_dwordx4 v[28:31], v[142:143], off offset:512
	v_mfma_f32_16x16x32_bf16 v[182:185], v[220:223], v[236:239], v[182:185]
	v_mfma_f32_16x16x32_bf16 v[186:189], v[220:223], v[240:243], v[186:189]
	v_mfma_f32_16x16x32_bf16 v[190:193], v[220:223], v[244:247], v[190:193]
	v_mfma_f32_16x16x32_bf16 v[150:153], v[220:223], v[248:251], v[150:153]
	v_mfma_f32_16x16x32_bf16 v[178:181], v[224:227], v[236:239], v[178:181]
	v_mfma_f32_16x16x32_bf16 v[194:197], v[224:227], v[240:243], v[194:197]
	v_mfma_f32_16x16x32_bf16 v[198:201], v[224:227], v[244:247], v[198:201]
	v_mfma_f32_16x16x32_bf16 v[154:157], v[224:227], v[248:251], v[154:157]
	v_mfma_f32_16x16x32_bf16 v[202:205], v[228:231], v[236:239], v[202:205]
	v_mfma_f32_16x16x32_bf16 v[212:215], v[228:231], v[240:243], v[212:215]
	v_mfma_f32_16x16x32_bf16 v[216:219], v[228:231], v[244:247], v[216:219]
	v_mfma_f32_16x16x32_bf16 v[158:161], v[228:231], v[248:251], v[158:161]
	v_mfma_f32_16x16x32_bf16 v[166:169], v[232:235], v[236:239], v[166:169]
	v_mfma_f32_16x16x32_bf16 v[170:173], v[232:235], v[240:243], v[170:173]
	v_mfma_f32_16x16x32_bf16 v[174:177], v[232:235], v[244:247], v[174:177]
	v_mfma_f32_16x16x32_bf16 v[162:165], v[232:235], v[248:251], v[162:165]
	ds_read_b128 v[220:223], v146
	ds_read_b128 v[224:227], v146 offset:2560
	ds_read_b128 v[228:231], v146 offset:5120
	ds_read_b128 v[232:235], v146 offset:7680
	ds_read_b128 v[236:239], v147
	ds_read_b128 v[240:243], v147 offset:2560
	ds_read_b128 v[244:247], v147 offset:5120
	ds_read_b128 v[248:251], v147 offset:7680
	s_waitcnt lgkmcnt(3)
	v_mfma_f32_16x16x32_bf16 v[182:185], v[220:223], v[236:239], v[182:185]
	s_waitcnt lgkmcnt(2)
	v_mfma_f32_16x16x32_bf16 v[186:189], v[220:223], v[240:243], v[186:189]
	s_waitcnt lgkmcnt(1)
	v_mfma_f32_16x16x32_bf16 v[190:193], v[220:223], v[244:247], v[190:193]
	s_waitcnt lgkmcnt(0)
	v_mfma_f32_16x16x32_bf16 v[150:153], v[220:223], v[248:251], v[150:153]
	v_mfma_f32_16x16x32_bf16 v[178:181], v[224:227], v[236:239], v[178:181]
	v_mfma_f32_16x16x32_bf16 v[194:197], v[224:227], v[240:243], v[194:197]
	v_mfma_f32_16x16x32_bf16 v[198:201], v[224:227], v[244:247], v[198:201]
	v_mfma_f32_16x16x32_bf16 v[154:157], v[224:227], v[248:251], v[154:157]
	v_mfma_f32_16x16x32_bf16 v[202:205], v[228:231], v[236:239], v[202:205]
	v_mfma_f32_16x16x32_bf16 v[212:215], v[228:231], v[240:243], v[212:215]
	v_mfma_f32_16x16x32_bf16 v[216:219], v[228:231], v[244:247], v[216:219]
	v_mfma_f32_16x16x32_bf16 v[158:161], v[228:231], v[248:251], v[158:161]
	v_mfma_f32_16x16x32_bf16 v[166:169], v[232:235], v[236:239], v[166:169]
	v_mfma_f32_16x16x32_bf16 v[170:173], v[232:235], v[240:243], v[170:173]
	v_mfma_f32_16x16x32_bf16 v[174:177], v[232:235], v[244:247], v[174:177]
	v_mfma_f32_16x16x32_bf16 v[162:165], v[232:235], v[248:251], v[162:165]
	ds_read_b128 v[220:223], v146 offset:64
	ds_read_b128 v[224:227], v146 offset:2624
	ds_read_b128 v[228:231], v146 offset:5184
	ds_read_b128 v[232:235], v146 offset:7744
	ds_read_b128 v[236:239], v147 offset:64
	ds_read_b128 v[240:243], v147 offset:2624
	ds_read_b128 v[244:247], v147 offset:5184
	ds_read_b128 v[248:251], v147 offset:7744
	s_waitcnt vmcnt(15)
	ds_write_b128 v145, v[56:59] offset:40960
	s_waitcnt vmcnt(14)
	ds_write_b128 v145, v[60:63] offset:46080
	s_waitcnt vmcnt(13)
	ds_write_b128 v145, v[44:47] offset:51200
	s_waitcnt vmcnt(12)
	ds_write_b128 v145, v[48:51] offset:56320
	s_waitcnt vmcnt(11)
	ds_write_b128 v145, v[52:55] offset:61440
	s_waitcnt vmcnt(10)
	ds_write_b128 v148, v[32:35] offset:5120
	s_waitcnt vmcnt(9)
	ds_write_b128 v148, v[36:39] offset:10240
	s_waitcnt vmcnt(8)
	ds_write_b128 v148, v[40:43] offset:15360
	s_waitcnt lgkmcnt(0)
	s_barrier
	global_load_dwordx4 v[56:59], v[128:129], off offset:640
	global_load_dwordx4 v[60:63], v[130:131], off offset:640
	global_load_dwordx4 v[44:47], v[132:133], off offset:640
	global_load_dwordx4 v[48:51], v[134:135], off offset:640
	global_load_dwordx4 v[52:55], v[136:137], off offset:640
	global_load_dwordx4 v[32:35], v[138:139], off offset:640
	global_load_dwordx4 v[36:39], v[140:141], off offset:640
	global_load_dwordx4 v[40:43], v[142:143], off offset:640
	v_mfma_f32_16x16x32_bf16 v[182:185], v[220:223], v[236:239], v[182:185]
	v_mfma_f32_16x16x32_bf16 v[186:189], v[220:223], v[240:243], v[186:189]
	v_mfma_f32_16x16x32_bf16 v[190:193], v[220:223], v[244:247], v[190:193]
	v_mfma_f32_16x16x32_bf16 v[150:153], v[220:223], v[248:251], v[150:153]
	v_mfma_f32_16x16x32_bf16 v[178:181], v[224:227], v[236:239], v[178:181]
	v_mfma_f32_16x16x32_bf16 v[194:197], v[224:227], v[240:243], v[194:197]
	v_mfma_f32_16x16x32_bf16 v[198:201], v[224:227], v[244:247], v[198:201]
	v_mfma_f32_16x16x32_bf16 v[154:157], v[224:227], v[248:251], v[154:157]
	v_mfma_f32_16x16x32_bf16 v[202:205], v[228:231], v[236:239], v[202:205]
	v_mfma_f32_16x16x32_bf16 v[212:215], v[228:231], v[240:243], v[212:215]
	v_mfma_f32_16x16x32_bf16 v[216:219], v[228:231], v[244:247], v[216:219]
	v_mfma_f32_16x16x32_bf16 v[158:161], v[228:231], v[248:251], v[158:161]
	v_mfma_f32_16x16x32_bf16 v[166:169], v[232:235], v[236:239], v[166:169]
	v_mfma_f32_16x16x32_bf16 v[170:173], v[232:235], v[240:243], v[170:173]
	v_mfma_f32_16x16x32_bf16 v[174:177], v[232:235], v[244:247], v[174:177]
	v_mfma_f32_16x16x32_bf16 v[162:165], v[232:235], v[248:251], v[162:165]
	ds_read_b128 v[220:223], v146 offset:40960
	ds_read_b128 v[224:227], v146 offset:43520
	ds_read_b128 v[228:231], v146 offset:46080
	ds_read_b128 v[232:235], v146 offset:48640
	ds_read_b128 v[236:239], v147 offset:40960
	ds_read_b128 v[240:243], v147 offset:43520
	ds_read_b128 v[244:247], v147 offset:46080
	ds_read_b128 v[248:251], v147 offset:48640
	s_waitcnt lgkmcnt(3)
	v_mfma_f32_16x16x32_bf16 v[182:185], v[220:223], v[236:239], v[182:185]
	s_waitcnt lgkmcnt(2)
	v_mfma_f32_16x16x32_bf16 v[186:189], v[220:223], v[240:243], v[186:189]
	s_waitcnt lgkmcnt(1)
	v_mfma_f32_16x16x32_bf16 v[190:193], v[220:223], v[244:247], v[190:193]
	s_waitcnt lgkmcnt(0)
	v_mfma_f32_16x16x32_bf16 v[150:153], v[220:223], v[248:251], v[150:153]
	v_mfma_f32_16x16x32_bf16 v[178:181], v[224:227], v[236:239], v[178:181]
	v_mfma_f32_16x16x32_bf16 v[194:197], v[224:227], v[240:243], v[194:197]
	v_mfma_f32_16x16x32_bf16 v[198:201], v[224:227], v[244:247], v[198:201]
	v_mfma_f32_16x16x32_bf16 v[154:157], v[224:227], v[248:251], v[154:157]
	v_mfma_f32_16x16x32_bf16 v[202:205], v[228:231], v[236:239], v[202:205]
	v_mfma_f32_16x16x32_bf16 v[212:215], v[228:231], v[240:243], v[212:215]
	v_mfma_f32_16x16x32_bf16 v[216:219], v[228:231], v[244:247], v[216:219]
	v_mfma_f32_16x16x32_bf16 v[158:161], v[228:231], v[248:251], v[158:161]
	v_mfma_f32_16x16x32_bf16 v[166:169], v[232:235], v[236:239], v[166:169]
	v_mfma_f32_16x16x32_bf16 v[170:173], v[232:235], v[240:243], v[170:173]
	v_mfma_f32_16x16x32_bf16 v[174:177], v[232:235], v[244:247], v[174:177]
	v_mfma_f32_16x16x32_bf16 v[162:165], v[232:235], v[248:251], v[162:165]
	ds_read_b128 v[220:223], v146 offset:41024
	ds_read_b128 v[224:227], v146 offset:43584
	ds_read_b128 v[228:231], v146 offset:46144
	ds_read_b128 v[232:235], v146 offset:48704
	ds_read_b128 v[236:239], v147 offset:41024
	ds_read_b128 v[240:243], v147 offset:43584
	ds_read_b128 v[244:247], v147 offset:46144
	ds_read_b128 v[248:251], v147 offset:48704
	s_waitcnt vmcnt(15)
	ds_write_b128 v145, v[0:3]
	s_waitcnt vmcnt(14)
	ds_write_b128 v145, v[4:7] offset:5120
	s_waitcnt vmcnt(13)
	ds_write_b128 v145, v[8:11] offset:10240
	s_waitcnt vmcnt(12)
	ds_write_b128 v145, v[12:15] offset:15360
	s_waitcnt vmcnt(11)
	ds_write_b128 v145, v[16:19] offset:20480
	s_waitcnt vmcnt(10)
	ds_write_b128 v145, v[20:23] offset:25600
	s_waitcnt vmcnt(9)
	ds_write_b128 v145, v[24:27] offset:30720
	s_waitcnt vmcnt(8)
	ds_write_b128 v145, v[28:31] offset:35840
	s_waitcnt lgkmcnt(0)
	s_barrier
	global_load_dwordx4 v[0:3], v[128:129], off offset:768
	global_load_dwordx4 v[4:7], v[130:131], off offset:768
	global_load_dwordx4 v[8:11], v[132:133], off offset:768
	global_load_dwordx4 v[12:15], v[134:135], off offset:768
	global_load_dwordx4 v[16:19], v[136:137], off offset:768
	global_load_dwordx4 v[20:23], v[138:139], off offset:768
	global_load_dwordx4 v[24:27], v[140:141], off offset:768
	global_load_dwordx4 v[28:31], v[142:143], off offset:768
	v_mfma_f32_16x16x32_bf16 v[182:185], v[220:223], v[236:239], v[182:185]
	v_mfma_f32_16x16x32_bf16 v[186:189], v[220:223], v[240:243], v[186:189]
	v_mfma_f32_16x16x32_bf16 v[190:193], v[220:223], v[244:247], v[190:193]
	v_mfma_f32_16x16x32_bf16 v[150:153], v[220:223], v[248:251], v[150:153]
	v_mfma_f32_16x16x32_bf16 v[178:181], v[224:227], v[236:239], v[178:181]
	v_mfma_f32_16x16x32_bf16 v[194:197], v[224:227], v[240:243], v[194:197]
	v_mfma_f32_16x16x32_bf16 v[198:201], v[224:227], v[244:247], v[198:201]
	v_mfma_f32_16x16x32_bf16 v[154:157], v[224:227], v[248:251], v[154:157]
	v_mfma_f32_16x16x32_bf16 v[202:205], v[228:231], v[236:239], v[202:205]
	v_mfma_f32_16x16x32_bf16 v[212:215], v[228:231], v[240:243], v[212:215]
	v_mfma_f32_16x16x32_bf16 v[216:219], v[228:231], v[244:247], v[216:219]
	v_mfma_f32_16x16x32_bf16 v[158:161], v[228:231], v[248:251], v[158:161]
	v_mfma_f32_16x16x32_bf16 v[166:169], v[232:235], v[236:239], v[166:169]
	v_mfma_f32_16x16x32_bf16 v[170:173], v[232:235], v[240:243], v[170:173]
	v_mfma_f32_16x16x32_bf16 v[174:177], v[232:235], v[244:247], v[174:177]
	v_mfma_f32_16x16x32_bf16 v[162:165], v[232:235], v[248:251], v[162:165]
	ds_read_b128 v[220:223], v146
	ds_read_b128 v[224:227], v146 offset:2560
	ds_read_b128 v[228:231], v146 offset:5120
	ds_read_b128 v[232:235], v146 offset:7680
	ds_read_b128 v[236:239], v147
	ds_read_b128 v[240:243], v147 offset:2560
	ds_read_b128 v[244:247], v147 offset:5120
	ds_read_b128 v[248:251], v147 offset:7680
	s_waitcnt lgkmcnt(3)
	v_mfma_f32_16x16x32_bf16 v[182:185], v[220:223], v[236:239], v[182:185]
	s_waitcnt lgkmcnt(2)
	v_mfma_f32_16x16x32_bf16 v[186:189], v[220:223], v[240:243], v[186:189]
	s_waitcnt lgkmcnt(1)
	v_mfma_f32_16x16x32_bf16 v[190:193], v[220:223], v[244:247], v[190:193]
	s_waitcnt lgkmcnt(0)
	v_mfma_f32_16x16x32_bf16 v[150:153], v[220:223], v[248:251], v[150:153]
	v_mfma_f32_16x16x32_bf16 v[178:181], v[224:227], v[236:239], v[178:181]
	v_mfma_f32_16x16x32_bf16 v[194:197], v[224:227], v[240:243], v[194:197]
	v_mfma_f32_16x16x32_bf16 v[198:201], v[224:227], v[244:247], v[198:201]
	v_mfma_f32_16x16x32_bf16 v[154:157], v[224:227], v[248:251], v[154:157]
	v_mfma_f32_16x16x32_bf16 v[202:205], v[228:231], v[236:239], v[202:205]
	v_mfma_f32_16x16x32_bf16 v[212:215], v[228:231], v[240:243], v[212:215]
	v_mfma_f32_16x16x32_bf16 v[216:219], v[228:231], v[244:247], v[216:219]
	v_mfma_f32_16x16x32_bf16 v[158:161], v[228:231], v[248:251], v[158:161]
	v_mfma_f32_16x16x32_bf16 v[166:169], v[232:235], v[236:239], v[166:169]
	v_mfma_f32_16x16x32_bf16 v[170:173], v[232:235], v[240:243], v[170:173]
	v_mfma_f32_16x16x32_bf16 v[174:177], v[232:235], v[244:247], v[174:177]
	v_mfma_f32_16x16x32_bf16 v[162:165], v[232:235], v[248:251], v[162:165]
	ds_read_b128 v[220:223], v146 offset:64
	ds_read_b128 v[224:227], v146 offset:2624
	ds_read_b128 v[228:231], v146 offset:5184
	ds_read_b128 v[232:235], v146 offset:7744
	ds_read_b128 v[236:239], v147 offset:64
	ds_read_b128 v[240:243], v147 offset:2624
	ds_read_b128 v[244:247], v147 offset:5184
	ds_read_b128 v[248:251], v147 offset:7744
	s_waitcnt vmcnt(15)
	ds_write_b128 v145, v[56:59] offset:40960
	s_waitcnt vmcnt(14)
	ds_write_b128 v145, v[60:63] offset:46080
	s_waitcnt vmcnt(13)
	ds_write_b128 v145, v[44:47] offset:51200
	s_waitcnt vmcnt(12)
	ds_write_b128 v145, v[48:51] offset:56320
	s_waitcnt vmcnt(11)
	ds_write_b128 v145, v[52:55] offset:61440
	s_waitcnt vmcnt(10)
	ds_write_b128 v148, v[32:35] offset:5120
	s_waitcnt vmcnt(9)
	ds_write_b128 v148, v[36:39] offset:10240
	s_waitcnt vmcnt(8)
	ds_write_b128 v148, v[40:43] offset:15360
	s_waitcnt lgkmcnt(0)
	s_barrier
	global_load_dwordx4 v[56:59], v[128:129], off offset:896
	global_load_dwordx4 v[60:63], v[130:131], off offset:896
	global_load_dwordx4 v[44:47], v[132:133], off offset:896
	global_load_dwordx4 v[48:51], v[134:135], off offset:896
	global_load_dwordx4 v[52:55], v[136:137], off offset:896
	global_load_dwordx4 v[32:35], v[138:139], off offset:896
	global_load_dwordx4 v[36:39], v[140:141], off offset:896
	global_load_dwordx4 v[40:43], v[142:143], off offset:896
	v_mfma_f32_16x16x32_bf16 v[182:185], v[220:223], v[236:239], v[182:185]
	v_mfma_f32_16x16x32_bf16 v[186:189], v[220:223], v[240:243], v[186:189]
	v_mfma_f32_16x16x32_bf16 v[190:193], v[220:223], v[244:247], v[190:193]
	v_mfma_f32_16x16x32_bf16 v[150:153], v[220:223], v[248:251], v[150:153]
	v_mfma_f32_16x16x32_bf16 v[178:181], v[224:227], v[236:239], v[178:181]
	v_mfma_f32_16x16x32_bf16 v[194:197], v[224:227], v[240:243], v[194:197]
	v_mfma_f32_16x16x32_bf16 v[198:201], v[224:227], v[244:247], v[198:201]
	v_mfma_f32_16x16x32_bf16 v[154:157], v[224:227], v[248:251], v[154:157]
	v_mfma_f32_16x16x32_bf16 v[202:205], v[228:231], v[236:239], v[202:205]
	v_mfma_f32_16x16x32_bf16 v[212:215], v[228:231], v[240:243], v[212:215]
	v_mfma_f32_16x16x32_bf16 v[216:219], v[228:231], v[244:247], v[216:219]
	v_mfma_f32_16x16x32_bf16 v[158:161], v[228:231], v[248:251], v[158:161]
	v_mfma_f32_16x16x32_bf16 v[166:169], v[232:235], v[236:239], v[166:169]
	v_mfma_f32_16x16x32_bf16 v[170:173], v[232:235], v[240:243], v[170:173]
	v_mfma_f32_16x16x32_bf16 v[174:177], v[232:235], v[244:247], v[174:177]
	v_mfma_f32_16x16x32_bf16 v[162:165], v[232:235], v[248:251], v[162:165]
	ds_read_b128 v[128:131], v146 offset:40960
	ds_read_b128 v[132:135], v146 offset:43520
	ds_read_b128 v[136:139], v146 offset:46080
	ds_read_b128 v[140:143], v146 offset:48640
	ds_read_b128 v[220:223], v147 offset:40960
	ds_read_b128 v[224:227], v147 offset:43520
	ds_read_b128 v[228:231], v147 offset:46080
	ds_read_b128 v[232:235], v147 offset:48640
	s_waitcnt lgkmcnt(3)
	v_mfma_f32_16x16x32_bf16 v[182:185], v[128:131], v[220:223], v[182:185]
	s_waitcnt lgkmcnt(2)
	v_mfma_f32_16x16x32_bf16 v[186:189], v[128:131], v[224:227], v[186:189]
	s_waitcnt lgkmcnt(1)
	v_mfma_f32_16x16x32_bf16 v[190:193], v[128:131], v[228:231], v[190:193]
	s_waitcnt lgkmcnt(0)
	v_mfma_f32_16x16x32_bf16 v[128:131], v[128:131], v[232:235], v[150:153]
	v_mfma_f32_16x16x32_bf16 v[150:153], v[132:135], v[220:223], v[178:181]
	v_mfma_f32_16x16x32_bf16 v[178:181], v[132:135], v[224:227], v[194:197]
	v_mfma_f32_16x16x32_bf16 v[194:197], v[132:135], v[228:231], v[198:201]
	v_mfma_f32_16x16x32_bf16 v[132:135], v[132:135], v[232:235], v[154:157]
	v_mfma_f32_16x16x32_bf16 v[154:157], v[136:139], v[220:223], v[202:205]
	v_mfma_f32_16x16x32_bf16 v[198:201], v[136:139], v[224:227], v[212:215]
	v_mfma_f32_16x16x32_bf16 v[202:205], v[136:139], v[228:231], v[216:219]
	v_mfma_f32_16x16x32_bf16 v[136:139], v[136:139], v[232:235], v[158:161]
	v_mfma_f32_16x16x32_bf16 v[158:161], v[140:143], v[220:223], v[166:169]
	v_mfma_f32_16x16x32_bf16 v[166:169], v[140:143], v[224:227], v[170:173]
	v_mfma_f32_16x16x32_bf16 v[170:173], v[140:143], v[228:231], v[174:177]
	v_mfma_f32_16x16x32_bf16 v[140:143], v[140:143], v[232:235], v[162:165]
	s_nop 2
	ds_read_b128 v[162:165], v146 offset:41024
	ds_read_b128 v[174:177], v146 offset:43584
	ds_read_b128 v[212:215], v146 offset:46144
	ds_read_b128 v[216:219], v146 offset:48704
	ds_read_b128 v[220:223], v147 offset:41024
	ds_read_b128 v[224:227], v147 offset:43584
	ds_read_b128 v[228:231], v147 offset:46144
	ds_read_b128 v[232:235], v147 offset:48704
	s_waitcnt vmcnt(15)
	ds_write_b128 v145, v[0:3]
	s_waitcnt vmcnt(14)
	ds_write_b128 v145, v[4:7] offset:5120
	s_waitcnt vmcnt(13)
	ds_write_b128 v145, v[8:11] offset:10240
	s_waitcnt vmcnt(12)
	ds_write_b128 v145, v[12:15] offset:15360
	s_waitcnt vmcnt(11)
	ds_write_b128 v145, v[16:19] offset:20480
	s_waitcnt vmcnt(10)
	ds_write_b128 v145, v[20:23] offset:25600
	s_waitcnt vmcnt(9)
	ds_write_b128 v145, v[24:27] offset:30720
	s_waitcnt vmcnt(8)
	ds_write_b128 v145, v[28:31] offset:35840
	s_waitcnt lgkmcnt(0)
	s_barrier
	ds_read_b128 v[0:3], v146
	ds_read_b128 v[4:7], v146 offset:2560
	ds_read_b128 v[8:11], v146 offset:5120
	ds_read_b128 v[12:15], v146 offset:7680
	ds_read_b128 v[16:19], v147
	ds_read_b128 v[20:23], v147 offset:2560
	ds_read_b128 v[24:27], v147 offset:5120
	ds_read_b128 v[28:31], v147 offset:7680
	v_mfma_f32_16x16x32_bf16 v[182:185], v[162:165], v[220:223], v[182:185]
	v_mfma_f32_16x16x32_bf16 v[186:189], v[162:165], v[224:227], v[186:189]
	v_mfma_f32_16x16x32_bf16 v[190:193], v[162:165], v[228:231], v[190:193]
	v_mfma_f32_16x16x32_bf16 v[128:131], v[162:165], v[232:235], v[128:131]
	v_mfma_f32_16x16x32_bf16 v[150:153], v[174:177], v[220:223], v[150:153]
	v_mfma_f32_16x16x32_bf16 v[162:165], v[174:177], v[224:227], v[178:181]
	v_mfma_f32_16x16x32_bf16 v[178:181], v[174:177], v[228:231], v[194:197]
	v_mfma_f32_16x16x32_bf16 v[132:135], v[174:177], v[232:235], v[132:135]
	v_mfma_f32_16x16x32_bf16 v[154:157], v[212:215], v[220:223], v[154:157]
	v_mfma_f32_16x16x32_bf16 v[174:177], v[212:215], v[224:227], v[198:201]
	v_mfma_f32_16x16x32_bf16 v[194:197], v[212:215], v[228:231], v[202:205]
	v_mfma_f32_16x16x32_bf16 v[136:139], v[212:215], v[232:235], v[136:139]
	v_mfma_f32_16x16x32_bf16 v[158:161], v[216:219], v[220:223], v[158:161]
	v_mfma_f32_16x16x32_bf16 v[166:169], v[216:219], v[224:227], v[166:169]
	v_mfma_f32_16x16x32_bf16 v[170:173], v[216:219], v[228:231], v[170:173]
	v_mfma_f32_16x16x32_bf16 v[140:143], v[216:219], v[232:235], v[140:143]
	s_waitcnt lgkmcnt(3)
	v_mfma_f32_16x16x32_bf16 v[182:185], v[0:3], v[16:19], v[182:185]
	s_waitcnt lgkmcnt(2)
	v_mfma_f32_16x16x32_bf16 v[186:189], v[0:3], v[20:23], v[186:189]
	s_waitcnt lgkmcnt(1)
	v_mfma_f32_16x16x32_bf16 v[190:193], v[0:3], v[24:27], v[190:193]
	s_waitcnt lgkmcnt(0)
	v_mfma_f32_16x16x32_bf16 v[0:3], v[0:3], v[28:31], v[128:131]
	v_mfma_f32_16x16x32_bf16 v[128:131], v[4:7], v[16:19], v[150:153]
	v_mfma_f32_16x16x32_bf16 v[150:153], v[4:7], v[20:23], v[162:165]
	v_mfma_f32_16x16x32_bf16 v[162:165], v[4:7], v[24:27], v[178:181]
	v_mfma_f32_16x16x32_bf16 v[4:7], v[4:7], v[28:31], v[132:135]
	v_mfma_f32_16x16x32_bf16 v[132:135], v[8:11], v[16:19], v[154:157]
	v_mfma_f32_16x16x32_bf16 v[154:157], v[8:11], v[20:23], v[174:177]
	v_mfma_f32_16x16x32_bf16 v[174:177], v[8:11], v[24:27], v[194:197]
	v_mfma_f32_16x16x32_bf16 v[8:11], v[8:11], v[28:31], v[136:139]
	v_mfma_f32_16x16x32_bf16 v[16:19], v[12:15], v[16:19], v[158:161]
	v_mfma_f32_16x16x32_bf16 v[20:23], v[12:15], v[20:23], v[166:169]
	v_mfma_f32_16x16x32_bf16 v[24:27], v[12:15], v[24:27], v[170:173]
	v_mfma_f32_16x16x32_bf16 v[12:15], v[12:15], v[28:31], v[140:143]
	ds_read_b128 v[28:31], v146 offset:64
	ds_read_b128 v[136:139], v146 offset:2624
	s_nop 0
	ds_read_b128 v[140:143], v146 offset:5184
	ds_read_b128 v[158:161], v146 offset:7744
	ds_read_b128 v[166:169], v147 offset:64
	ds_read_b128 v[170:173], v147 offset:2624
	ds_read_b128 v[178:181], v147 offset:5184
	ds_read_b128 v[194:197], v147 offset:7744
	s_waitcnt vmcnt(7)
	ds_write_b128 v145, v[56:59] offset:40960
	s_waitcnt vmcnt(6)
	ds_write_b128 v145, v[60:63] offset:46080
	s_waitcnt vmcnt(5)
	ds_write_b128 v145, v[44:47] offset:51200
	s_waitcnt vmcnt(4)
	ds_write_b128 v145, v[48:51] offset:56320
	s_waitcnt vmcnt(3)
	ds_write_b128 v145, v[52:55] offset:61440
	s_waitcnt vmcnt(2)
	ds_write_b128 v148, v[32:35] offset:5120
	s_waitcnt vmcnt(1)
	ds_write_b128 v148, v[36:39] offset:10240
	s_waitcnt vmcnt(0)
	ds_write_b128 v148, v[40:43] offset:15360
	s_waitcnt lgkmcnt(0)
	s_barrier
	ds_read_b128 v[32:35], v146 offset:40960
	ds_read_b128 v[36:39], v146 offset:43520
	ds_read_b128 v[40:43], v146 offset:46080
	ds_read_b128 v[44:47], v146 offset:48640
	ds_read_b128 v[48:51], v147 offset:40960
	ds_read_b128 v[52:55], v147 offset:43520
	ds_read_b128 v[56:59], v147 offset:46080
	ds_read_b128 v[60:63], v147 offset:48640
	v_mfma_f32_16x16x32_bf16 v[182:185], v[28:31], v[166:169], v[182:185]
	v_mfma_f32_16x16x32_bf16 v[186:189], v[28:31], v[170:173], v[186:189]
	v_mfma_f32_16x16x32_bf16 v[190:193], v[28:31], v[178:181], v[190:193]
	v_mfma_f32_16x16x32_bf16 v[0:3], v[28:31], v[194:197], v[0:3]
	v_mfma_f32_16x16x32_bf16 v[28:31], v[136:139], v[166:169], v[128:131]
	v_mfma_f32_16x16x32_bf16 v[128:131], v[136:139], v[170:173], v[150:153]
	v_mfma_f32_16x16x32_bf16 v[150:153], v[136:139], v[178:181], v[162:165]
	v_mfma_f32_16x16x32_bf16 v[4:7], v[136:139], v[194:197], v[4:7]
	v_mfma_f32_16x16x32_bf16 v[132:135], v[140:143], v[166:169], v[132:135]
	v_mfma_f32_16x16x32_bf16 v[136:139], v[140:143], v[170:173], v[154:157]
	v_mfma_f32_16x16x32_bf16 v[154:157], v[140:143], v[178:181], v[174:177]
	v_mfma_f32_16x16x32_bf16 v[8:11], v[140:143], v[194:197], v[8:11]
	v_mfma_f32_16x16x32_bf16 v[16:19], v[158:161], v[166:169], v[16:19]
	v_mfma_f32_16x16x32_bf16 v[20:23], v[158:161], v[170:173], v[20:23]
	v_mfma_f32_16x16x32_bf16 v[24:27], v[158:161], v[178:181], v[24:27]
	v_mfma_f32_16x16x32_bf16 v[12:15], v[158:161], v[194:197], v[12:15]
	s_waitcnt lgkmcnt(3)
	v_mfma_f32_16x16x32_bf16 v[140:143], v[32:35], v[48:51], v[182:185]
	s_waitcnt lgkmcnt(2)
	v_mfma_f32_16x16x32_bf16 v[158:161], v[32:35], v[52:55], v[186:189]
	s_waitcnt lgkmcnt(1)
	v_mfma_f32_16x16x32_bf16 v[162:165], v[32:35], v[56:59], v[190:193]
	s_waitcnt lgkmcnt(0)
	v_mfma_f32_16x16x32_bf16 v[0:3], v[32:35], v[60:63], v[0:3]
	v_mfma_f32_16x16x32_bf16 v[28:31], v[36:39], v[48:51], v[28:31]
	v_mfma_f32_16x16x32_bf16 v[32:35], v[36:39], v[52:55], v[128:131]
	v_mfma_f32_16x16x32_bf16 v[128:131], v[36:39], v[56:59], v[150:153]
	v_mfma_f32_16x16x32_bf16 v[4:7], v[36:39], v[60:63], v[4:7]
	v_mfma_f32_16x16x32_bf16 v[36:39], v[40:43], v[48:51], v[132:135]
	v_mfma_f32_16x16x32_bf16 v[132:135], v[40:43], v[52:55], v[136:139]
	v_mfma_f32_16x16x32_bf16 v[136:139], v[40:43], v[56:59], v[154:157]
	v_mfma_f32_16x16x32_bf16 v[8:11], v[40:43], v[60:63], v[8:11]
	v_mfma_f32_16x16x32_bf16 v[16:19], v[44:47], v[48:51], v[16:19]
	v_mfma_f32_16x16x32_bf16 v[20:23], v[44:47], v[52:55], v[20:23]
	v_mfma_f32_16x16x32_bf16 v[24:27], v[44:47], v[56:59], v[24:27]
	v_mfma_f32_16x16x32_bf16 v[12:15], v[44:47], v[60:63], v[12:15]
	ds_read_b128 v[40:43], v146 offset:41024
	ds_read_b128 v[44:47], v146 offset:43584
	ds_read_b128 v[48:51], v146 offset:46144
	ds_read_b128 v[52:55], v146 offset:48704
	ds_read_b128 v[56:59], v147 offset:41024
	ds_read_b128 v[60:63], v147 offset:43584
	ds_read_b128 v[148:151], v147 offset:46144
	ds_read_b128 v[152:155], v147 offset:48704
	s_waitcnt lgkmcnt(0)
	s_barrier
	v_mfma_f32_16x16x32_bf16 v[140:143], v[40:43], v[56:59], v[140:143]
	v_mfma_f32_16x16x32_bf16 v[156:159], v[40:43], v[60:63], v[158:161]
	v_mfma_f32_16x16x32_bf16 v[160:163], v[40:43], v[148:151], v[162:165]
	v_mfma_f32_16x16x32_bf16 v[0:3], v[40:43], v[152:155], v[0:3]
	v_mfma_f32_16x16x32_bf16 v[28:31], v[44:47], v[56:59], v[28:31]
	v_mfma_f32_16x16x32_bf16 v[32:35], v[44:47], v[60:63], v[32:35]
	v_mfma_f32_16x16x32_bf16 v[40:43], v[44:47], v[148:151], v[128:131]
	v_mfma_f32_16x16x32_bf16 v[4:7], v[44:47], v[152:155], v[4:7]
	v_mfma_f32_16x16x32_bf16 v[36:39], v[48:51], v[56:59], v[36:39]
	v_mfma_f32_16x16x32_bf16 v[44:47], v[48:51], v[60:63], v[132:135]
	v_mfma_f32_16x16x32_bf16 v[128:131], v[48:51], v[148:151], v[136:139]
	v_mfma_f32_16x16x32_bf16 v[8:11], v[48:51], v[152:155], v[8:11]
	v_mov_b32_e32 v48, v211
	s_nop 0
	v_lshrrev_b32_e32 v50, 2, v48
	v_lshrrev_b32_e32 v49, 1, v48
	v_and_b32_e32 v50, 12, v50
	v_and_or_b32 v49, v49, s43, v50
	v_and_b32_e32 v48, 0x4f, v48
	v_lshlrev_b32_e32 v48, 2, v48
	v_mul_lo_u32 v49, v49, s22
	v_add3_u32 v48, 0, v48, v49
	v_mfma_f32_16x16x32_bf16 v[16:19], v[52:55], v[56:59], v[16:19]
	v_add_u32_e32 v49, 0x400, v48
	ds_write2_b32 v48, v140, v156 offset1:16
	ds_write2_b32 v48, v141, v157 offset0:132 offset1:148
	ds_write2_b32 v49, v142, v158 offset0:8 offset1:24
	ds_write2_b32 v49, v143, v159 offset0:140 offset1:156
	ds_write2_b32 v48, v160, v0 offset0:32 offset1:48
	ds_write2_b32 v48, v161, v1 offset0:164 offset1:180
	ds_write2_b32 v49, v162, v2 offset0:40 offset1:56
	ds_write2_b32 v49, v163, v3 offset0:172 offset1:188
	v_mfma_f32_16x16x32_bf16 v[20:23], v[52:55], v[60:63], v[20:23]
	v_add_u32_e32 v0, 0x2000, v48
	v_add_u32_e32 v1, 0x2400, v48
	ds_write2_b32 v0, v28, v32 offset0:64 offset1:80
	ds_write2_b32 v0, v29, v33 offset0:196 offset1:212
	v_mfma_f32_16x16x32_bf16 v[24:27], v[52:55], v[148:151], v[24:27]
	ds_write2_b32 v1, v30, v34 offset0:72 offset1:88
	ds_write2_b32 v1, v31, v35 offset0:204 offset1:220
	ds_write2_b32 v0, v40, v4 offset0:96 offset1:112
	ds_write2_b32 v0, v41, v5 offset0:228 offset1:244
	ds_write2_b32 v1, v42, v6 offset0:104 offset1:120
	ds_write2_b32 v1, v43, v7 offset0:236 offset1:252
	v_add_u32_e32 v0, 0x4000, v48
	v_add_u32_e32 v1, 0x4400, v48
	v_mfma_f32_16x16x32_bf16 v[12:15], v[52:55], v[152:155], v[12:15]
	v_add_u32_e32 v2, 0x4800, v48
	ds_write2_b32 v0, v36, v44 offset0:128 offset1:144
	ds_write2_b32 v1, v37, v45 offset0:4 offset1:20
	ds_write2_b32 v1, v38, v46 offset0:136 offset1:152
	ds_write2_b32 v2, v39, v47 offset0:12 offset1:28
	ds_write2_b32 v0, v128, v8 offset0:160 offset1:176
	ds_write2_b32 v1, v129, v9 offset0:36 offset1:52
	ds_write2_b32 v1, v130, v10 offset0:168 offset1:184
	ds_write2_b32 v2, v131, v11 offset0:44 offset1:60
	v_add_u32_e32 v0, 0x6000, v48
	v_add_u32_e32 v1, 0x6400, v48
	v_add_u32_e32 v2, 0x6800, v48
	ds_write2_b32 v0, v16, v20 offset0:192 offset1:208
	ds_write2_b32 v1, v17, v21 offset0:68 offset1:84
	ds_write2_b32 v1, v18, v22 offset0:200 offset1:216
	ds_write2_b32 v2, v19, v23 offset0:76 offset1:92
	ds_write2_b32 v0, v24, v12 offset0:224 offset1:240
	ds_write2_b32 v1, v25, v13 offset0:100 offset1:116
	ds_write2_b32 v1, v26, v14 offset0:232 offset1:248
	ds_write2_b32 v2, v27, v15 offset0:108 offset1:124
	v_mov_b32_e32 v0, v211
	s_waitcnt lgkmcnt(0)
	s_barrier
	s_nop 0
	v_ashrrev_i32_e32 v8, 4, v0
	v_lshlrev_b32_e32 v1, 5, v0
	v_and_b32_e32 v11, 15, v0
	v_and_b32_e32 v9, 0x1e0, v1
	v_lshlrev_b32_e32 v4, 5, v11
	v_mul_lo_u32 v10, v8, s22
	global_load_dwordx4 v[0:3], v4, s[20:21] offset:16
	s_nop 0
	global_load_dwordx4 v[4:7], v4, s[20:21]
	v_add3_u32 v10, 0, v9, v10
	v_mad_i64_i32 v[8:9], s[20:21], v8, s39, 0
	s_add_u32 s20, s2, s19
	v_lshl_or_b32 v8, v11, 4, v8
	s_addc_u32 s21, s3, s16
	v_lshl_add_u64 v[8:9], s[20:21], 0, v[8:9]
	s_mov_b32 s20, 0xcc01000
	v_add_co_u32_e32 v12, vcc, s20, v8
	s_add_u32 s6, s6, 0x1000
	s_nop 0
	v_addc_co_u32_e32 v13, vcc, 0, v9, vcc
	global_load_dwordx4 v[12:15], v[12:13], off offset:2048 nt
	s_mov_b32 s20, 0xcc31000
	v_add_co_u32_e32 v32, vcc, s20, v8
	s_nop 1
	v_addc_co_u32_e32 v33, vcc, 0, v9, vcc
	global_load_dwordx4 v[32:35], v[32:33], off offset:2048 nt
	s_mov_b32 s20, 0xcc61000
	v_add_co_u32_e32 v36, vcc, s20, v8
	s_nop 1
	v_addc_co_u32_e32 v37, vcc, 0, v9, vcc
	global_load_dwordx4 v[36:39], v[36:37], off offset:2048 nt
	s_mov_b32 s20, 0xcc91000
	v_add_co_u32_e32 v40, vcc, s20, v8
	s_nop 1
	v_addc_co_u32_e32 v41, vcc, 0, v9, vcc
	global_load_dwordx4 v[40:43], v[40:41], off offset:2048 nt
	s_mov_b32 s20, 0xccc1000
	v_add_co_u32_e32 v44, vcc, s20, v8
	s_nop 1
	v_addc_co_u32_e32 v45, vcc, 0, v9, vcc
	global_load_dwordx4 v[44:47], v[44:45], off offset:2048 nt
	s_mov_b32 s20, 0xccf1000
	v_add_co_u32_e32 v48, vcc, s20, v8
	s_nop 1
	v_addc_co_u32_e32 v49, vcc, 0, v9, vcc
	global_load_dwordx4 v[48:51], v[48:49], off offset:2048 nt
	s_mov_b32 s20, 0xcd21000
	v_add_co_u32_e32 v52, vcc, s20, v8
	s_nop 1
	v_addc_co_u32_e32 v53, vcc, 0, v9, vcc
	global_load_dwordx4 v[52:55], v[52:53], off offset:2048 nt
	s_mov_b32 s20, 0xcd51000
	v_add_co_u32_e32 v56, vcc, s20, v8
	s_nop 1
	v_addc_co_u32_e32 v57, vcc, 0, v9, vcc
	global_load_dwordx4 v[56:59], v[56:57], off offset:2048 nt
	s_addc_u32 s7, s7, 0
	s_add_u32 s19, s19, 0x800
	s_addc_u32 s16, s16, 0
	s_add_u32 s15, s15, 0x400
	s_addc_u32 s13, s13, 0
	s_add_u32 s8, s8, 0x100000
	s_addc_u32 s9, s9, 0
	s_cmpk_eq_i32 s6, 0x3000
	s_waitcnt vmcnt(7)
	v_lshlrev_b32_e32 v11, 16, v12
	v_add_f32_e32 v11, v4, v11
	v_and_b32_e32 v12, 0xffff0000, v12
	v_mul_f32_e32 v11, 0xbfb8aa3b, v11
	v_exp_f32_e32 v20, v11
	v_add_f32_e32 v11, v5, v12
	v_mul_f32_e32 v11, 0xbfb8aa3b, v11
	v_exp_f32_e32 v21, v11
	v_lshlrev_b32_e32 v22, 16, v13
	v_and_b32_e32 v23, 0xffff0000, v13
	v_lshlrev_b32_e32 v24, 16, v14
	v_and_b32_e32 v25, 0xffff0000, v14
	v_lshlrev_b32_e32 v26, 16, v15
	v_and_b32_e32 v27, 0xffff0000, v15
	ds_read_b128 v[12:15], v10
	ds_read_b128 v[16:19], v10 offset:16
	v_pk_add_f32 v[20:21], v[20:21], 1.0 op_sel_hi:[1,0]
	s_waitcnt lgkmcnt(1)
	v_div_scale_f32 v11, s[20:21], v21, v21, v13
	v_rcp_f32_e32 v28, v11
	s_nop 0
	v_fma_f32 v29, -v11, v28, 1.0
	v_fmac_f32_e32 v28, v29, v28
	v_div_scale_f32 v29, vcc, v13, v21, v13
	v_mul_f32_e32 v30, v29, v28
	v_fma_f32 v31, -v11, v30, v29
	v_fmac_f32_e32 v30, v31, v28
	v_fma_f32 v11, -v11, v30, v29
	v_div_fmas_f32 v11, v11, v28, v30
	v_div_fixup_f32 v13, v11, v21, v13
	v_div_scale_f32 v11, s[20:21], v20, v20, v12
	v_rcp_f32_e32 v21, v11
	s_nop 0
	v_fma_f32 v28, -v11, v21, 1.0
	v_fmac_f32_e32 v21, v28, v21
	v_div_scale_f32 v28, vcc, v12, v20, v12
	v_mul_f32_e32 v29, v28, v21
	v_fma_f32 v30, -v11, v29, v28
	v_fmac_f32_e32 v29, v30, v21
	v_fma_f32 v11, -v11, v29, v28
	v_div_fmas_f32 v11, v11, v21, v29
	v_div_fixup_f32 v12, v11, v20, v12
	v_add_f32_e32 v11, v6, v22
	v_mul_f32_e32 v11, 0xbfb8aa3b, v11
	v_pk_add_f32 v[126:127], v[126:127], v[12:13]
	v_exp_f32_e32 v12, v11
	v_add_f32_e32 v11, v7, v23
	v_mul_f32_e32 v11, 0xbfb8aa3b, v11
	v_exp_f32_e32 v13, v11
	s_nop 0
	v_pk_add_f32 v[12:13], v[12:13], 1.0 op_sel_hi:[1,0]
	s_nop 0
	v_div_scale_f32 v11, s[20:21], v13, v13, v15
	v_rcp_f32_e32 v20, v11
	s_nop 0
	v_fma_f32 v21, -v11, v20, 1.0
	v_fmac_f32_e32 v20, v21, v20
	v_div_scale_f32 v21, vcc, v15, v13, v15
	v_mul_f32_e32 v22, v21, v20
	v_fma_f32 v23, -v11, v22, v21
	v_fmac_f32_e32 v22, v23, v20
	v_fma_f32 v11, -v11, v22, v21
	v_div_fmas_f32 v11, v11, v20, v22
	v_div_fixup_f32 v13, v11, v13, v15
	v_div_scale_f32 v11, s[20:21], v12, v12, v14
	v_rcp_f32_e32 v15, v11
	s_nop 0
	v_fma_f32 v20, -v11, v15, 1.0
	v_fmac_f32_e32 v15, v20, v15
	v_div_scale_f32 v20, vcc, v14, v12, v14
	v_mul_f32_e32 v21, v20, v15
	v_fma_f32 v22, -v11, v21, v20
	v_fmac_f32_e32 v21, v22, v15
	v_fma_f32 v11, -v11, v21, v20
	v_div_fmas_f32 v11, v11, v15, v21
	v_div_fixup_f32 v12, v11, v12, v14
	v_add_f32_e32 v11, v0, v24
	v_mul_f32_e32 v11, 0xbfb8aa3b, v11
	v_pk_add_f32 v[124:125], v[124:125], v[12:13]
	v_exp_f32_e32 v12, v11
	v_add_f32_e32 v11, v1, v25
	v_mul_f32_e32 v11, 0xbfb8aa3b, v11
	v_exp_f32_e32 v13, v11
	s_nop 0
	v_pk_add_f32 v[12:13], v[12:13], 1.0 op_sel_hi:[1,0]
	s_waitcnt lgkmcnt(0)
	v_div_scale_f32 v11, s[20:21], v13, v13, v17
	v_rcp_f32_e32 v14, v11
	s_nop 0
	v_fma_f32 v15, -v11, v14, 1.0
	v_fmac_f32_e32 v14, v15, v14
	v_div_scale_f32 v15, vcc, v17, v13, v17
	v_mul_f32_e32 v20, v15, v14
	v_fma_f32 v21, -v11, v20, v15
	v_fmac_f32_e32 v20, v21, v14
	v_fma_f32 v11, -v11, v20, v15
	v_div_fmas_f32 v11, v11, v14, v20
	v_div_fixup_f32 v13, v11, v13, v17
	v_div_scale_f32 v11, s[20:21], v12, v12, v16
	v_rcp_f32_e32 v14, v11
	s_nop 0
	v_fma_f32 v15, -v11, v14, 1.0
	v_fmac_f32_e32 v14, v15, v14
	v_div_scale_f32 v15, vcc, v16, v12, v16
	v_mul_f32_e32 v17, v15, v14
	v_fma_f32 v20, -v11, v17, v15
	v_fmac_f32_e32 v17, v20, v14
	v_fma_f32 v11, -v11, v17, v15
	v_div_fmas_f32 v11, v11, v14, v17
	v_div_fixup_f32 v12, v11, v12, v16
	v_add_f32_e32 v11, v2, v26
	v_mul_f32_e32 v11, 0xbfb8aa3b, v11
	v_pk_add_f32 v[120:121], v[120:121], v[12:13]
	v_exp_f32_e32 v12, v11
	v_add_f32_e32 v11, v3, v27
	v_mul_f32_e32 v11, 0xbfb8aa3b, v11
	v_exp_f32_e32 v13, v11
	s_nop 0
	v_pk_add_f32 v[12:13], v[12:13], 1.0 op_sel_hi:[1,0]
	s_nop 0
	v_div_scale_f32 v11, s[20:21], v13, v13, v19
	v_rcp_f32_e32 v14, v11
	s_nop 0
	v_fma_f32 v15, -v11, v14, 1.0
	v_fmac_f32_e32 v14, v15, v14
	v_div_scale_f32 v15, vcc, v19, v13, v19
	v_mul_f32_e32 v16, v15, v14
	v_fma_f32 v17, -v11, v16, v15
	v_fmac_f32_e32 v16, v17, v14
	v_fma_f32 v11, -v11, v16, v15
	v_div_fmas_f32 v11, v11, v14, v16
	v_div_fixup_f32 v13, v11, v13, v19
	v_div_scale_f32 v11, s[20:21], v12, v12, v18
	v_rcp_f32_e32 v14, v11
	s_mov_b32 s20, 0xcc31000
	v_fma_f32 v15, -v11, v14, 1.0
	v_fmac_f32_e32 v14, v15, v14
	v_div_scale_f32 v15, vcc, v18, v12, v18
	v_mul_f32_e32 v16, v15, v14
	v_fma_f32 v17, -v11, v16, v15
	v_fmac_f32_e32 v16, v17, v14
	v_fma_f32 v11, -v11, v16, v15
	v_div_fmas_f32 v11, v11, v14, v16
	v_div_fixup_f32 v12, v11, v12, v18
	v_pk_add_f32 v[104:105], v[104:105], v[12:13]
	s_waitcnt vmcnt(6)
	v_mov_b32_e32 v12, v32
	v_mov_b32_e32 v13, v33
	v_mov_b32_e32 v14, v34
	v_mov_b32_e32 v15, v35
	v_lshlrev_b32_e32 v11, 16, v12
	v_add_f32_e32 v11, v4, v11
	v_and_b32_e32 v12, 0xffff0000, v12
	v_mul_f32_e32 v11, 0xbfb8aa3b, v11
	v_exp_f32_e32 v16, v11
	v_add_f32_e32 v11, v5, v12
	v_mul_f32_e32 v11, 0xbfb8aa3b, v11
	v_lshlrev_b32_e32 v18, 16, v13
	v_and_b32_e32 v19, 0xffff0000, v13
	v_lshlrev_b32_e32 v20, 16, v14
	v_and_b32_e32 v21, 0xffff0000, v14
	v_lshlrev_b32_e32 v22, 16, v15
	v_and_b32_e32 v23, 0xffff0000, v15
	v_exp_f32_e32 v17, v11
	ds_read_b128 v[12:15], v10 offset:8448
	v_pk_add_f32 v[16:17], v[16:17], 1.0 op_sel_hi:[1,0]
	s_waitcnt lgkmcnt(0)
	v_div_scale_f32 v11, s[20:21], v17, v17, v13
	v_rcp_f32_e32 v24, v11
	s_nop 0
	v_fma_f32 v25, -v11, v24, 1.0
	v_fmac_f32_e32 v24, v25, v24
	v_div_scale_f32 v25, vcc, v13, v17, v13
	v_mul_f32_e32 v26, v25, v24
	v_fma_f32 v27, -v11, v26, v25
	v_fmac_f32_e32 v26, v27, v24
	v_fma_f32 v11, -v11, v26, v25
	v_div_fmas_f32 v11, v11, v24, v26
	v_div_fixup_f32 v13, v11, v17, v13
	v_div_scale_f32 v11, s[20:21], v16, v16, v12
	v_rcp_f32_e32 v17, v11
	s_nop 0
	v_fma_f32 v24, -v11, v17, 1.0
	v_fmac_f32_e32 v17, v24, v17
	v_div_scale_f32 v24, vcc, v12, v16, v12
	v_mul_f32_e32 v25, v24, v17
	v_fma_f32 v26, -v11, v25, v24
	v_fmac_f32_e32 v25, v26, v17
	v_fma_f32 v11, -v11, v25, v24
	v_div_fmas_f32 v11, v11, v17, v25
	v_div_fixup_f32 v12, v11, v16, v12
	v_add_f32_e32 v11, v6, v18
	v_mul_f32_e32 v11, 0xbfb8aa3b, v11
	v_pk_add_f32 v[122:123], v[122:123], v[12:13]
	v_exp_f32_e32 v12, v11
	v_add_f32_e32 v11, v7, v19
	v_mul_f32_e32 v11, 0xbfb8aa3b, v11
	v_exp_f32_e32 v13, v11
	s_nop 0
	v_pk_add_f32 v[12:13], v[12:13], 1.0 op_sel_hi:[1,0]
	s_nop 0
	v_div_scale_f32 v11, s[20:21], v13, v13, v15
	v_rcp_f32_e32 v16, v11
	s_nop 0
	v_fma_f32 v17, -v11, v16, 1.0
	v_fmac_f32_e32 v16, v17, v16
	v_div_scale_f32 v17, vcc, v15, v13, v15
	v_mul_f32_e32 v18, v17, v16
	v_fma_f32 v19, -v11, v18, v17
	v_fmac_f32_e32 v18, v19, v16
	v_fma_f32 v11, -v11, v18, v17
	v_div_fmas_f32 v11, v11, v16, v18
	v_div_fixup_f32 v13, v11, v13, v15
	v_div_scale_f32 v11, s[20:21], v12, v12, v14
	v_rcp_f32_e32 v15, v11
	s_nop 0
	v_fma_f32 v16, -v11, v15, 1.0
	v_fmac_f32_e32 v15, v16, v15
	v_div_scale_f32 v16, vcc, v14, v12, v14
	v_mul_f32_e32 v17, v16, v15
	v_fma_f32 v18, -v11, v17, v16
	v_fmac_f32_e32 v17, v18, v15
	v_fma_f32 v11, -v11, v17, v16
	v_div_fmas_f32 v11, v11, v15, v17
	v_div_fixup_f32 v12, v11, v12, v14
	v_add_f32_e32 v11, v0, v20
	v_mul_f32_e32 v11, 0xbfb8aa3b, v11
	v_exp_f32_e32 v16, v11
	v_add_f32_e32 v11, v1, v21
	v_mul_f32_e32 v11, 0xbfb8aa3b, v11
	v_pk_add_f32 v[118:119], v[118:119], v[12:13]
	v_exp_f32_e32 v17, v11
	ds_read_b128 v[12:15], v10 offset:8464
	v_pk_add_f32 v[16:17], v[16:17], 1.0 op_sel_hi:[1,0]
	s_waitcnt lgkmcnt(0)
	v_div_scale_f32 v11, s[20:21], v17, v17, v13
	v_rcp_f32_e32 v18, v11
	s_nop 0
	v_fma_f32 v19, -v11, v18, 1.0
	v_fmac_f32_e32 v18, v19, v18
	v_div_scale_f32 v19, vcc, v13, v17, v13
	v_mul_f32_e32 v20, v19, v18
	v_fma_f32 v21, -v11, v20, v19
	v_fmac_f32_e32 v20, v21, v18
	v_fma_f32 v11, -v11, v20, v19
	v_div_fmas_f32 v11, v11, v18, v20
	v_div_fixup_f32 v13, v11, v17, v13
	v_div_scale_f32 v11, s[20:21], v16, v16, v12
	v_rcp_f32_e32 v17, v11
	s_nop 0
	v_fma_f32 v18, -v11, v17, 1.0
	v_fmac_f32_e32 v17, v18, v17
	v_div_scale_f32 v18, vcc, v12, v16, v12
	v_mul_f32_e32 v19, v18, v17
	v_fma_f32 v20, -v11, v19, v18
	v_fmac_f32_e32 v19, v20, v17
	v_fma_f32 v11, -v11, v19, v18
	v_div_fmas_f32 v11, v11, v17, v19
	v_div_fixup_f32 v12, v11, v16, v12
	v_add_f32_e32 v11, v2, v22
	v_mul_f32_e32 v11, 0xbfb8aa3b, v11
	v_pk_add_f32 v[114:115], v[114:115], v[12:13]
	v_exp_f32_e32 v12, v11
	v_add_f32_e32 v11, v3, v23
	v_mul_f32_e32 v11, 0xbfb8aa3b, v11
	v_exp_f32_e32 v13, v11
	s_nop 0
	v_pk_add_f32 v[12:13], v[12:13], 1.0 op_sel_hi:[1,0]
	s_nop 0
	v_div_scale_f32 v11, s[20:21], v13, v13, v15
	v_rcp_f32_e32 v16, v11
	s_nop 0
	v_fma_f32 v17, -v11, v16, 1.0
	v_fmac_f32_e32 v16, v17, v16
	v_div_scale_f32 v17, vcc, v15, v13, v15
	v_mul_f32_e32 v18, v17, v16
	v_fma_f32 v19, -v11, v18, v17
	v_fmac_f32_e32 v18, v19, v16
	v_fma_f32 v11, -v11, v18, v17
	v_div_fmas_f32 v11, v11, v16, v18
	v_div_fixup_f32 v13, v11, v13, v15
	v_div_scale_f32 v11, s[20:21], v12, v12, v14
	v_rcp_f32_e32 v15, v11
	s_mov_b32 s20, 0xcc61000
	v_fma_f32 v16, -v11, v15, 1.0
	v_fmac_f32_e32 v15, v16, v15
	v_div_scale_f32 v16, vcc, v14, v12, v14
	v_mul_f32_e32 v17, v16, v15
	v_fma_f32 v18, -v11, v17, v16
	v_fmac_f32_e32 v17, v18, v15
	v_fma_f32 v11, -v11, v17, v16
	v_div_fmas_f32 v11, v11, v15, v17
	v_div_fixup_f32 v12, v11, v12, v14
	v_pk_add_f32 v[110:111], v[110:111], v[12:13]
	s_waitcnt vmcnt(5)
	v_mov_b32_e32 v12, v36
	v_mov_b32_e32 v13, v37
	v_mov_b32_e32 v14, v38
	v_mov_b32_e32 v15, v39
	v_lshlrev_b32_e32 v11, 16, v12
	v_add_f32_e32 v11, v4, v11
	v_and_b32_e32 v12, 0xffff0000, v12
	v_mul_f32_e32 v11, 0xbfb8aa3b, v11
	v_exp_f32_e32 v16, v11
	v_add_f32_e32 v11, v5, v12
	v_mul_f32_e32 v11, 0xbfb8aa3b, v11
	v_lshlrev_b32_e32 v18, 16, v13
	v_and_b32_e32 v19, 0xffff0000, v13
	v_lshlrev_b32_e32 v20, 16, v14
	v_and_b32_e32 v21, 0xffff0000, v14
	v_lshlrev_b32_e32 v22, 16, v15
	v_and_b32_e32 v23, 0xffff0000, v15
	v_exp_f32_e32 v17, v11
	ds_read_b128 v[12:15], v10 offset:16896
	v_pk_add_f32 v[16:17], v[16:17], 1.0 op_sel_hi:[1,0]
	s_waitcnt lgkmcnt(0)
	v_div_scale_f32 v11, s[20:21], v17, v17, v13
	v_rcp_f32_e32 v24, v11
	s_nop 0
	v_fma_f32 v25, -v11, v24, 1.0
	v_fmac_f32_e32 v24, v25, v24
	v_div_scale_f32 v25, vcc, v13, v17, v13
	v_mul_f32_e32 v26, v25, v24
	v_fma_f32 v27, -v11, v26, v25
	v_fmac_f32_e32 v26, v27, v24
	v_fma_f32 v11, -v11, v26, v25
	v_div_fmas_f32 v11, v11, v24, v26
	v_div_fixup_f32 v13, v11, v17, v13
	v_div_scale_f32 v11, s[20:21], v16, v16, v12
	v_rcp_f32_e32 v17, v11
	s_nop 0
	v_fma_f32 v24, -v11, v17, 1.0
	v_fmac_f32_e32 v17, v24, v17
	v_div_scale_f32 v24, vcc, v12, v16, v12
	v_mul_f32_e32 v25, v24, v17
	v_fma_f32 v26, -v11, v25, v24
	v_fmac_f32_e32 v25, v26, v17
	v_fma_f32 v11, -v11, v25, v24
	v_div_fmas_f32 v11, v11, v17, v25
	v_div_fixup_f32 v12, v11, v16, v12
	v_add_f32_e32 v11, v6, v18
	v_mul_f32_e32 v11, 0xbfb8aa3b, v11
	v_pk_add_f32 v[116:117], v[116:117], v[12:13]
	v_exp_f32_e32 v12, v11
	v_add_f32_e32 v11, v7, v19
	v_mul_f32_e32 v11, 0xbfb8aa3b, v11
	v_exp_f32_e32 v13, v11
	s_nop 0
	v_pk_add_f32 v[12:13], v[12:13], 1.0 op_sel_hi:[1,0]
	s_nop 0
	v_div_scale_f32 v11, s[20:21], v13, v13, v15
	v_rcp_f32_e32 v16, v11
	s_nop 0
	v_fma_f32 v17, -v11, v16, 1.0
	v_fmac_f32_e32 v16, v17, v16
	v_div_scale_f32 v17, vcc, v15, v13, v15
	v_mul_f32_e32 v18, v17, v16
	v_fma_f32 v19, -v11, v18, v17
	v_fmac_f32_e32 v18, v19, v16
	v_fma_f32 v11, -v11, v18, v17
	v_div_fmas_f32 v11, v11, v16, v18
	v_div_fixup_f32 v13, v11, v13, v15
	v_div_scale_f32 v11, s[20:21], v12, v12, v14
	v_rcp_f32_e32 v15, v11
	s_nop 0
	v_fma_f32 v16, -v11, v15, 1.0
	v_fmac_f32_e32 v15, v16, v15
	v_div_scale_f32 v16, vcc, v14, v12, v14
	v_mul_f32_e32 v17, v16, v15
	v_fma_f32 v18, -v11, v17, v16
	v_fmac_f32_e32 v17, v18, v15
	v_fma_f32 v11, -v11, v17, v16
	v_div_fmas_f32 v11, v11, v15, v17
	v_div_fixup_f32 v12, v11, v12, v14
	v_add_f32_e32 v11, v0, v20
	v_mul_f32_e32 v11, 0xbfb8aa3b, v11
	v_exp_f32_e32 v16, v11
	v_add_f32_e32 v11, v1, v21
	v_mul_f32_e32 v11, 0xbfb8aa3b, v11
	v_pk_add_f32 v[112:113], v[112:113], v[12:13]
	v_exp_f32_e32 v17, v11
	ds_read_b128 v[12:15], v10 offset:16912
	v_pk_add_f32 v[16:17], v[16:17], 1.0 op_sel_hi:[1,0]
	s_waitcnt lgkmcnt(0)
	v_div_scale_f32 v11, s[20:21], v17, v17, v13
	v_rcp_f32_e32 v18, v11
	s_nop 0
	v_fma_f32 v19, -v11, v18, 1.0
	v_fmac_f32_e32 v18, v19, v18
	v_div_scale_f32 v19, vcc, v13, v17, v13
	v_mul_f32_e32 v20, v19, v18
	v_fma_f32 v21, -v11, v20, v19
	v_fmac_f32_e32 v20, v21, v18
	v_fma_f32 v11, -v11, v20, v19
	v_div_fmas_f32 v11, v11, v18, v20
	v_div_fixup_f32 v13, v11, v17, v13
	v_div_scale_f32 v11, s[20:21], v16, v16, v12
	v_rcp_f32_e32 v17, v11
	s_nop 0
	v_fma_f32 v18, -v11, v17, 1.0
	v_fmac_f32_e32 v17, v18, v17
	v_div_scale_f32 v18, vcc, v12, v16, v12
	v_mul_f32_e32 v19, v18, v17
	v_fma_f32 v20, -v11, v19, v18
	v_fmac_f32_e32 v19, v20, v17
	v_fma_f32 v11, -v11, v19, v18
	v_div_fmas_f32 v11, v11, v17, v19
	v_div_fixup_f32 v12, v11, v16, v12
	v_add_f32_e32 v11, v2, v22
	v_mul_f32_e32 v11, 0xbfb8aa3b, v11
	v_pk_add_f32 v[106:107], v[106:107], v[12:13]
	v_exp_f32_e32 v12, v11
	v_add_f32_e32 v11, v3, v23
	v_mul_f32_e32 v11, 0xbfb8aa3b, v11
	v_exp_f32_e32 v13, v11
	s_nop 0
	v_pk_add_f32 v[12:13], v[12:13], 1.0 op_sel_hi:[1,0]
	s_nop 0
	v_div_scale_f32 v11, s[20:21], v13, v13, v15
	v_rcp_f32_e32 v16, v11
	s_nop 0
	v_fma_f32 v17, -v11, v16, 1.0
	v_fmac_f32_e32 v16, v17, v16
	v_div_scale_f32 v17, vcc, v15, v13, v15
	v_mul_f32_e32 v18, v17, v16
	v_fma_f32 v19, -v11, v18, v17
	v_fmac_f32_e32 v18, v19, v16
	v_fma_f32 v11, -v11, v18, v17
	v_div_fmas_f32 v11, v11, v16, v18
	v_div_fixup_f32 v13, v11, v13, v15
	v_div_scale_f32 v11, s[20:21], v12, v12, v14
	v_rcp_f32_e32 v15, v11
	s_mov_b32 s20, 0xcc91000
	v_fma_f32 v16, -v11, v15, 1.0
	v_fmac_f32_e32 v15, v16, v15
	v_div_scale_f32 v16, vcc, v14, v12, v14
	v_mul_f32_e32 v17, v16, v15
	v_fma_f32 v18, -v11, v17, v16
	v_fmac_f32_e32 v17, v18, v15
	v_fma_f32 v11, -v11, v17, v16
	v_div_fmas_f32 v11, v11, v15, v17
	v_div_fixup_f32 v12, v11, v12, v14
	v_pk_add_f32 v[100:101], v[100:101], v[12:13]
	s_waitcnt vmcnt(4)
	v_mov_b32_e32 v12, v40
	v_mov_b32_e32 v13, v41
	v_mov_b32_e32 v14, v42
	v_mov_b32_e32 v15, v43
	v_lshlrev_b32_e32 v11, 16, v12
	v_add_f32_e32 v11, v4, v11
	v_and_b32_e32 v12, 0xffff0000, v12
	v_mul_f32_e32 v11, 0xbfb8aa3b, v11
	v_exp_f32_e32 v16, v11
	v_add_f32_e32 v11, v5, v12
	v_mul_f32_e32 v11, 0xbfb8aa3b, v11
	v_lshlrev_b32_e32 v18, 16, v13
	v_and_b32_e32 v19, 0xffff0000, v13
	v_lshlrev_b32_e32 v20, 16, v14
	v_and_b32_e32 v21, 0xffff0000, v14
	v_lshlrev_b32_e32 v22, 16, v15
	v_and_b32_e32 v23, 0xffff0000, v15
	v_exp_f32_e32 v17, v11
	ds_read_b128 v[12:15], v10 offset:25344
	v_pk_add_f32 v[16:17], v[16:17], 1.0 op_sel_hi:[1,0]
	s_waitcnt lgkmcnt(0)
	v_div_scale_f32 v11, s[20:21], v17, v17, v13
	v_rcp_f32_e32 v24, v11
	s_nop 0
	v_fma_f32 v25, -v11, v24, 1.0
	v_fmac_f32_e32 v24, v25, v24
	v_div_scale_f32 v25, vcc, v13, v17, v13
	v_mul_f32_e32 v26, v25, v24
	v_fma_f32 v27, -v11, v26, v25
	v_fmac_f32_e32 v26, v27, v24
	v_fma_f32 v11, -v11, v26, v25
	v_div_fmas_f32 v11, v11, v24, v26
	v_div_fixup_f32 v13, v11, v17, v13
	v_div_scale_f32 v11, s[20:21], v16, v16, v12
	v_rcp_f32_e32 v17, v11
	s_nop 0
	v_fma_f32 v24, -v11, v17, 1.0
	v_fmac_f32_e32 v17, v24, v17
	v_div_scale_f32 v24, vcc, v12, v16, v12
	v_mul_f32_e32 v25, v24, v17
	v_fma_f32 v26, -v11, v25, v24
	v_fmac_f32_e32 v25, v26, v17
	v_fma_f32 v11, -v11, v25, v24
	v_div_fmas_f32 v11, v11, v17, v25
	v_div_fixup_f32 v12, v11, v16, v12
	v_add_f32_e32 v11, v6, v18
	v_mul_f32_e32 v11, 0xbfb8aa3b, v11
	v_pk_add_f32 v[108:109], v[108:109], v[12:13]
	v_exp_f32_e32 v12, v11
	v_add_f32_e32 v11, v7, v19
	v_mul_f32_e32 v11, 0xbfb8aa3b, v11
	v_exp_f32_e32 v13, v11
	s_nop 0
	v_pk_add_f32 v[12:13], v[12:13], 1.0 op_sel_hi:[1,0]
	s_nop 0
	v_div_scale_f32 v11, s[20:21], v13, v13, v15
	v_rcp_f32_e32 v16, v11
	s_nop 0
	v_fma_f32 v17, -v11, v16, 1.0
	v_fmac_f32_e32 v16, v17, v16
	v_div_scale_f32 v17, vcc, v15, v13, v15
	v_mul_f32_e32 v18, v17, v16
	v_fma_f32 v19, -v11, v18, v17
	v_fmac_f32_e32 v18, v19, v16
	v_fma_f32 v11, -v11, v18, v17
	v_div_fmas_f32 v11, v11, v16, v18
	v_div_fixup_f32 v13, v11, v13, v15
	v_div_scale_f32 v11, s[20:21], v12, v12, v14
	v_rcp_f32_e32 v15, v11
	s_nop 0
	v_fma_f32 v16, -v11, v15, 1.0
	v_fmac_f32_e32 v15, v16, v15
	v_div_scale_f32 v16, vcc, v14, v12, v14
	v_mul_f32_e32 v17, v16, v15
	v_fma_f32 v18, -v11, v17, v16
	v_fmac_f32_e32 v17, v18, v15
	v_fma_f32 v11, -v11, v17, v16
	v_div_fmas_f32 v11, v11, v15, v17
	v_div_fixup_f32 v12, v11, v12, v14
	v_add_f32_e32 v11, v0, v20
	v_mul_f32_e32 v11, 0xbfb8aa3b, v11
	v_exp_f32_e32 v16, v11
	v_add_f32_e32 v11, v1, v21
	v_mul_f32_e32 v11, 0xbfb8aa3b, v11
	v_pk_add_f32 v[102:103], v[102:103], v[12:13]
	v_exp_f32_e32 v17, v11
	ds_read_b128 v[12:15], v10 offset:25360
	v_pk_add_f32 v[16:17], v[16:17], 1.0 op_sel_hi:[1,0]
	s_waitcnt lgkmcnt(0)
	v_div_scale_f32 v11, s[20:21], v17, v17, v13
	v_rcp_f32_e32 v18, v11
	s_nop 0
	v_fma_f32 v19, -v11, v18, 1.0
	v_fmac_f32_e32 v18, v19, v18
	v_div_scale_f32 v19, vcc, v13, v17, v13
	v_mul_f32_e32 v20, v19, v18
	v_fma_f32 v21, -v11, v20, v19
	v_fmac_f32_e32 v20, v21, v18
	v_fma_f32 v11, -v11, v20, v19
	v_div_fmas_f32 v11, v11, v18, v20
	v_div_fixup_f32 v13, v11, v17, v13
	v_div_scale_f32 v11, s[20:21], v16, v16, v12
	v_rcp_f32_e32 v17, v11
	s_nop 0
	v_fma_f32 v18, -v11, v17, 1.0
	v_fmac_f32_e32 v17, v18, v17
	v_div_scale_f32 v18, vcc, v12, v16, v12
	v_mul_f32_e32 v19, v18, v17
	v_fma_f32 v20, -v11, v19, v18
	v_fmac_f32_e32 v19, v20, v17
	v_fma_f32 v11, -v11, v19, v18
	v_div_fmas_f32 v11, v11, v17, v19
	v_div_fixup_f32 v12, v11, v16, v12
	v_add_f32_e32 v11, v2, v22
	v_mul_f32_e32 v11, 0xbfb8aa3b, v11
	v_pk_add_f32 v[96:97], v[96:97], v[12:13]
	v_exp_f32_e32 v12, v11
	v_add_f32_e32 v11, v3, v23
	v_mul_f32_e32 v11, 0xbfb8aa3b, v11
	v_exp_f32_e32 v13, v11
	s_nop 0
	v_pk_add_f32 v[12:13], v[12:13], 1.0 op_sel_hi:[1,0]
	s_nop 0
	v_div_scale_f32 v11, s[20:21], v13, v13, v15
	v_rcp_f32_e32 v16, v11
	s_nop 0
	v_fma_f32 v17, -v11, v16, 1.0
	v_fmac_f32_e32 v16, v17, v16
	v_div_scale_f32 v17, vcc, v15, v13, v15
	v_mul_f32_e32 v18, v17, v16
	v_fma_f32 v19, -v11, v18, v17
	v_fmac_f32_e32 v18, v19, v16
	v_fma_f32 v11, -v11, v18, v17
	v_div_fmas_f32 v11, v11, v16, v18
	v_div_fixup_f32 v13, v11, v13, v15
	v_div_scale_f32 v11, s[20:21], v12, v12, v14
	v_rcp_f32_e32 v15, v11
	s_mov_b32 s20, 0xccc1000
	v_fma_f32 v16, -v11, v15, 1.0
	v_fmac_f32_e32 v15, v16, v15
	v_div_scale_f32 v16, vcc, v14, v12, v14
	v_mul_f32_e32 v17, v16, v15
	v_fma_f32 v18, -v11, v17, v16
	v_fmac_f32_e32 v17, v18, v15
	v_fma_f32 v11, -v11, v17, v16
	v_div_fmas_f32 v11, v11, v15, v17
	v_div_fixup_f32 v12, v11, v12, v14
	v_pk_add_f32 v[92:93], v[92:93], v[12:13]
	s_waitcnt vmcnt(3)
	v_mov_b32_e32 v12, v44
	v_mov_b32_e32 v13, v45
	v_mov_b32_e32 v14, v46
	v_mov_b32_e32 v15, v47
	v_lshlrev_b32_e32 v11, 16, v12
	v_add_f32_e32 v11, v4, v11
	v_and_b32_e32 v12, 0xffff0000, v12
	v_mul_f32_e32 v11, 0xbfb8aa3b, v11
	v_exp_f32_e32 v16, v11
	v_add_f32_e32 v11, v5, v12
	v_mul_f32_e32 v11, 0xbfb8aa3b, v11
	v_lshlrev_b32_e32 v18, 16, v13
	v_and_b32_e32 v19, 0xffff0000, v13
	v_lshlrev_b32_e32 v20, 16, v14
	v_and_b32_e32 v21, 0xffff0000, v14
	v_lshlrev_b32_e32 v22, 16, v15
	v_and_b32_e32 v23, 0xffff0000, v15
	v_exp_f32_e32 v17, v11
	ds_read_b128 v[12:15], v10 offset:33792
	v_pk_add_f32 v[16:17], v[16:17], 1.0 op_sel_hi:[1,0]
	s_waitcnt lgkmcnt(0)
	v_div_scale_f32 v11, s[20:21], v17, v17, v13
	v_rcp_f32_e32 v24, v11
	s_nop 0
	v_fma_f32 v25, -v11, v24, 1.0
	v_fmac_f32_e32 v24, v25, v24
	v_div_scale_f32 v25, vcc, v13, v17, v13
	v_mul_f32_e32 v26, v25, v24
	v_fma_f32 v27, -v11, v26, v25
	v_fmac_f32_e32 v26, v27, v24
	v_fma_f32 v11, -v11, v26, v25
	v_div_fmas_f32 v11, v11, v24, v26
	v_div_fixup_f32 v13, v11, v17, v13
	v_div_scale_f32 v11, s[20:21], v16, v16, v12
	v_rcp_f32_e32 v17, v11
	s_nop 0
	v_fma_f32 v24, -v11, v17, 1.0
	v_fmac_f32_e32 v17, v24, v17
	v_div_scale_f32 v24, vcc, v12, v16, v12
	v_mul_f32_e32 v25, v24, v17
	v_fma_f32 v26, -v11, v25, v24
	v_fmac_f32_e32 v25, v26, v17
	v_fma_f32 v11, -v11, v25, v24
	v_div_fmas_f32 v11, v11, v17, v25
	v_div_fixup_f32 v12, v11, v16, v12
	v_add_f32_e32 v11, v6, v18
	v_mul_f32_e32 v11, 0xbfb8aa3b, v11
	v_pk_add_f32 v[98:99], v[98:99], v[12:13]
	v_exp_f32_e32 v12, v11
	v_add_f32_e32 v11, v7, v19
	v_mul_f32_e32 v11, 0xbfb8aa3b, v11
	v_exp_f32_e32 v13, v11
	s_nop 0
	v_pk_add_f32 v[12:13], v[12:13], 1.0 op_sel_hi:[1,0]
	s_nop 0
	v_div_scale_f32 v11, s[20:21], v13, v13, v15
	v_rcp_f32_e32 v16, v11
	s_nop 0
	v_fma_f32 v17, -v11, v16, 1.0
	v_fmac_f32_e32 v16, v17, v16
	v_div_scale_f32 v17, vcc, v15, v13, v15
	v_mul_f32_e32 v18, v17, v16
	v_fma_f32 v19, -v11, v18, v17
	v_fmac_f32_e32 v18, v19, v16
	v_fma_f32 v11, -v11, v18, v17
	v_div_fmas_f32 v11, v11, v16, v18
	v_div_fixup_f32 v13, v11, v13, v15
	v_div_scale_f32 v11, s[20:21], v12, v12, v14
	v_rcp_f32_e32 v15, v11
	s_nop 0
	v_fma_f32 v16, -v11, v15, 1.0
	v_fmac_f32_e32 v15, v16, v15
	v_div_scale_f32 v16, vcc, v14, v12, v14
	v_mul_f32_e32 v17, v16, v15
	v_fma_f32 v18, -v11, v17, v16
	v_fmac_f32_e32 v17, v18, v15
	v_fma_f32 v11, -v11, v17, v16
	v_div_fmas_f32 v11, v11, v15, v17
	v_div_fixup_f32 v12, v11, v12, v14
	v_add_f32_e32 v11, v0, v20
	v_mul_f32_e32 v11, 0xbfb8aa3b, v11
	v_exp_f32_e32 v16, v11
	v_add_f32_e32 v11, v1, v21
	v_mul_f32_e32 v11, 0xbfb8aa3b, v11
	v_pk_add_f32 v[94:95], v[94:95], v[12:13]
	v_exp_f32_e32 v17, v11
	ds_read_b128 v[12:15], v10 offset:33808
	v_pk_add_f32 v[16:17], v[16:17], 1.0 op_sel_hi:[1,0]
	s_waitcnt lgkmcnt(0)
	v_div_scale_f32 v11, s[20:21], v17, v17, v13
	v_rcp_f32_e32 v18, v11
	s_nop 0
	v_fma_f32 v19, -v11, v18, 1.0
	v_fmac_f32_e32 v18, v19, v18
	v_div_scale_f32 v19, vcc, v13, v17, v13
	v_mul_f32_e32 v20, v19, v18
	v_fma_f32 v21, -v11, v20, v19
	v_fmac_f32_e32 v20, v21, v18
	v_fma_f32 v11, -v11, v20, v19
	v_div_fmas_f32 v11, v11, v18, v20
	v_div_fixup_f32 v13, v11, v17, v13
	v_div_scale_f32 v11, s[20:21], v16, v16, v12
	v_rcp_f32_e32 v17, v11
	s_nop 0
	v_fma_f32 v18, -v11, v17, 1.0
	v_fmac_f32_e32 v17, v18, v17
	v_div_scale_f32 v18, vcc, v12, v16, v12
	v_mul_f32_e32 v19, v18, v17
	v_fma_f32 v20, -v11, v19, v18
	v_fmac_f32_e32 v19, v20, v17
	v_fma_f32 v11, -v11, v19, v18
	v_div_fmas_f32 v11, v11, v17, v19
	v_div_fixup_f32 v12, v11, v16, v12
	v_add_f32_e32 v11, v2, v22
	v_mul_f32_e32 v11, 0xbfb8aa3b, v11
	v_pk_add_f32 v[88:89], v[88:89], v[12:13]
	v_exp_f32_e32 v12, v11
	v_add_f32_e32 v11, v3, v23
	v_mul_f32_e32 v11, 0xbfb8aa3b, v11
	v_exp_f32_e32 v13, v11
	s_nop 0
	v_pk_add_f32 v[12:13], v[12:13], 1.0 op_sel_hi:[1,0]
	s_nop 0
	v_div_scale_f32 v11, s[20:21], v13, v13, v15
	v_rcp_f32_e32 v16, v11
	s_nop 0
	v_fma_f32 v17, -v11, v16, 1.0
	v_fmac_f32_e32 v16, v17, v16
	v_div_scale_f32 v17, vcc, v15, v13, v15
	v_mul_f32_e32 v18, v17, v16
	v_fma_f32 v19, -v11, v18, v17
	v_fmac_f32_e32 v18, v19, v16
	v_fma_f32 v11, -v11, v18, v17
	v_div_fmas_f32 v11, v11, v16, v18
	v_div_fixup_f32 v13, v11, v13, v15
	v_div_scale_f32 v11, s[20:21], v12, v12, v14
	v_rcp_f32_e32 v15, v11
	s_mov_b32 s20, 0xccf1000
	v_fma_f32 v16, -v11, v15, 1.0
	v_fmac_f32_e32 v15, v16, v15
	v_div_scale_f32 v16, vcc, v14, v12, v14
	v_mul_f32_e32 v17, v16, v15
	v_fma_f32 v18, -v11, v17, v16
	v_fmac_f32_e32 v17, v18, v15
	v_fma_f32 v11, -v11, v17, v16
	v_div_fmas_f32 v11, v11, v15, v17
	v_div_fixup_f32 v12, v11, v12, v14
	v_pk_add_f32 v[84:85], v[84:85], v[12:13]
	s_waitcnt vmcnt(2)
	v_mov_b32_e32 v12, v48
	v_mov_b32_e32 v13, v49
	v_mov_b32_e32 v14, v50
	v_mov_b32_e32 v15, v51
	v_lshlrev_b32_e32 v11, 16, v12
	v_add_f32_e32 v11, v4, v11
	v_and_b32_e32 v12, 0xffff0000, v12
	v_mul_f32_e32 v11, 0xbfb8aa3b, v11
	v_exp_f32_e32 v16, v11
	v_add_f32_e32 v11, v5, v12
	v_mul_f32_e32 v11, 0xbfb8aa3b, v11
	v_lshlrev_b32_e32 v18, 16, v13
	v_and_b32_e32 v19, 0xffff0000, v13
	v_lshlrev_b32_e32 v20, 16, v14
	v_and_b32_e32 v21, 0xffff0000, v14
	v_lshlrev_b32_e32 v22, 16, v15
	v_and_b32_e32 v23, 0xffff0000, v15
	v_exp_f32_e32 v17, v11
	ds_read_b128 v[12:15], v10 offset:42240
	v_pk_add_f32 v[16:17], v[16:17], 1.0 op_sel_hi:[1,0]
	s_waitcnt lgkmcnt(0)
	v_div_scale_f32 v11, s[20:21], v17, v17, v13
	v_rcp_f32_e32 v24, v11
	s_nop 0
	v_fma_f32 v25, -v11, v24, 1.0
	v_fmac_f32_e32 v24, v25, v24
	v_div_scale_f32 v25, vcc, v13, v17, v13
	v_mul_f32_e32 v26, v25, v24
	v_fma_f32 v27, -v11, v26, v25
	v_fmac_f32_e32 v26, v27, v24
	v_fma_f32 v11, -v11, v26, v25
	v_div_fmas_f32 v11, v11, v24, v26
	v_div_fixup_f32 v13, v11, v17, v13
	v_div_scale_f32 v11, s[20:21], v16, v16, v12
	v_rcp_f32_e32 v17, v11
	s_nop 0
	v_fma_f32 v24, -v11, v17, 1.0
	v_fmac_f32_e32 v17, v24, v17
	v_div_scale_f32 v24, vcc, v12, v16, v12
	v_mul_f32_e32 v25, v24, v17
	v_fma_f32 v26, -v11, v25, v24
	v_fmac_f32_e32 v25, v26, v17
	v_fma_f32 v11, -v11, v25, v24
	v_div_fmas_f32 v11, v11, v17, v25
	v_div_fixup_f32 v12, v11, v16, v12
	v_add_f32_e32 v11, v6, v18
	v_mul_f32_e32 v11, 0xbfb8aa3b, v11
	v_pk_add_f32 v[90:91], v[90:91], v[12:13]
	v_exp_f32_e32 v12, v11
	v_add_f32_e32 v11, v7, v19
	v_mul_f32_e32 v11, 0xbfb8aa3b, v11
	v_exp_f32_e32 v13, v11
	s_nop 0
	v_pk_add_f32 v[12:13], v[12:13], 1.0 op_sel_hi:[1,0]
	s_nop 0
	v_div_scale_f32 v11, s[20:21], v13, v13, v15
	v_rcp_f32_e32 v16, v11
	s_nop 0
	v_fma_f32 v17, -v11, v16, 1.0
	v_fmac_f32_e32 v16, v17, v16
	v_div_scale_f32 v17, vcc, v15, v13, v15
	v_mul_f32_e32 v18, v17, v16
	v_fma_f32 v19, -v11, v18, v17
	v_fmac_f32_e32 v18, v19, v16
	v_fma_f32 v11, -v11, v18, v17
	v_div_fmas_f32 v11, v11, v16, v18
	v_div_fixup_f32 v13, v11, v13, v15
	v_div_scale_f32 v11, s[20:21], v12, v12, v14
	v_rcp_f32_e32 v15, v11
	s_nop 0
	v_fma_f32 v16, -v11, v15, 1.0
	v_fmac_f32_e32 v15, v16, v15
	v_div_scale_f32 v16, vcc, v14, v12, v14
	v_mul_f32_e32 v17, v16, v15
	v_fma_f32 v18, -v11, v17, v16
	v_fmac_f32_e32 v17, v18, v15
	v_fma_f32 v11, -v11, v17, v16
	v_div_fmas_f32 v11, v11, v15, v17
	v_div_fixup_f32 v12, v11, v12, v14
	v_add_f32_e32 v11, v0, v20
	v_mul_f32_e32 v11, 0xbfb8aa3b, v11
	v_exp_f32_e32 v16, v11
	v_add_f32_e32 v11, v1, v21
	v_mul_f32_e32 v11, 0xbfb8aa3b, v11
	v_pk_add_f32 v[86:87], v[86:87], v[12:13]
	v_exp_f32_e32 v17, v11
	ds_read_b128 v[12:15], v10 offset:42256
	v_pk_add_f32 v[16:17], v[16:17], 1.0 op_sel_hi:[1,0]
	s_waitcnt lgkmcnt(0)
	v_div_scale_f32 v11, s[20:21], v17, v17, v13
	v_rcp_f32_e32 v18, v11
	s_nop 0
	v_fma_f32 v19, -v11, v18, 1.0
	v_fmac_f32_e32 v18, v19, v18
	v_div_scale_f32 v19, vcc, v13, v17, v13
	v_mul_f32_e32 v20, v19, v18
	v_fma_f32 v21, -v11, v20, v19
	v_fmac_f32_e32 v20, v21, v18
	v_fma_f32 v11, -v11, v20, v19
	v_div_fmas_f32 v11, v11, v18, v20
	v_div_fixup_f32 v13, v11, v17, v13
	v_div_scale_f32 v11, s[20:21], v16, v16, v12
	v_rcp_f32_e32 v17, v11
	s_nop 0
	v_fma_f32 v18, -v11, v17, 1.0
	v_fmac_f32_e32 v17, v18, v17
	v_div_scale_f32 v18, vcc, v12, v16, v12
	v_mul_f32_e32 v19, v18, v17
	v_fma_f32 v20, -v11, v19, v18
	v_fmac_f32_e32 v19, v20, v17
	v_fma_f32 v11, -v11, v19, v18
	v_div_fmas_f32 v11, v11, v17, v19
	v_div_fixup_f32 v12, v11, v16, v12
	v_add_f32_e32 v11, v2, v22
	v_mul_f32_e32 v11, 0xbfb8aa3b, v11
	v_pk_add_f32 v[82:83], v[82:83], v[12:13]
	v_exp_f32_e32 v12, v11
	v_add_f32_e32 v11, v3, v23
	v_mul_f32_e32 v11, 0xbfb8aa3b, v11
	v_exp_f32_e32 v13, v11
	s_nop 0
	v_pk_add_f32 v[12:13], v[12:13], 1.0 op_sel_hi:[1,0]
	s_nop 0
	v_div_scale_f32 v11, s[20:21], v13, v13, v15
	v_rcp_f32_e32 v16, v11
	s_nop 0
	v_fma_f32 v17, -v11, v16, 1.0
	v_fmac_f32_e32 v16, v17, v16
	v_div_scale_f32 v17, vcc, v15, v13, v15
	v_mul_f32_e32 v18, v17, v16
	v_fma_f32 v19, -v11, v18, v17
	v_fmac_f32_e32 v18, v19, v16
	v_fma_f32 v11, -v11, v18, v17
	v_div_fmas_f32 v11, v11, v16, v18
	v_div_fixup_f32 v13, v11, v13, v15
	v_div_scale_f32 v11, s[20:21], v12, v12, v14
	v_rcp_f32_e32 v15, v11
	s_mov_b32 s20, 0xcd21000
	v_fma_f32 v16, -v11, v15, 1.0
	v_fmac_f32_e32 v15, v16, v15
	v_div_scale_f32 v16, vcc, v14, v12, v14
	v_mul_f32_e32 v17, v16, v15
	v_fma_f32 v18, -v11, v17, v16
	v_fmac_f32_e32 v17, v18, v15
	v_fma_f32 v11, -v11, v17, v16
	v_div_fmas_f32 v11, v11, v15, v17
	v_div_fixup_f32 v12, v11, v12, v14
	v_pk_add_f32 v[78:79], v[78:79], v[12:13]
	s_waitcnt vmcnt(1)
	v_mov_b32_e32 v12, v52
	v_mov_b32_e32 v13, v53
	v_mov_b32_e32 v14, v54
	v_mov_b32_e32 v15, v55
	v_lshlrev_b32_e32 v11, 16, v12
	v_add_f32_e32 v11, v4, v11
	v_and_b32_e32 v12, 0xffff0000, v12
	v_mul_f32_e32 v11, 0xbfb8aa3b, v11
	v_exp_f32_e32 v16, v11
	v_add_f32_e32 v11, v5, v12
	v_mul_f32_e32 v11, 0xbfb8aa3b, v11
	v_lshlrev_b32_e32 v18, 16, v13
	v_and_b32_e32 v19, 0xffff0000, v13
	v_lshlrev_b32_e32 v20, 16, v14
	v_and_b32_e32 v21, 0xffff0000, v14
	v_lshlrev_b32_e32 v22, 16, v15
	v_and_b32_e32 v23, 0xffff0000, v15
	v_exp_f32_e32 v17, v11
	ds_read_b128 v[12:15], v10 offset:50688
	v_pk_add_f32 v[16:17], v[16:17], 1.0 op_sel_hi:[1,0]
	s_waitcnt lgkmcnt(0)
	v_div_scale_f32 v11, s[20:21], v17, v17, v13
	v_rcp_f32_e32 v24, v11
	s_nop 0
	v_fma_f32 v25, -v11, v24, 1.0
	v_fmac_f32_e32 v24, v25, v24
	v_div_scale_f32 v25, vcc, v13, v17, v13
	v_mul_f32_e32 v26, v25, v24
	v_fma_f32 v27, -v11, v26, v25
	v_fmac_f32_e32 v26, v27, v24
	v_fma_f32 v11, -v11, v26, v25
	v_div_fmas_f32 v11, v11, v24, v26
	v_div_fixup_f32 v13, v11, v17, v13
	v_div_scale_f32 v11, s[20:21], v16, v16, v12
	v_rcp_f32_e32 v17, v11
	s_nop 0
	v_fma_f32 v24, -v11, v17, 1.0
	v_fmac_f32_e32 v17, v24, v17
	v_div_scale_f32 v24, vcc, v12, v16, v12
	v_mul_f32_e32 v25, v24, v17
	v_fma_f32 v26, -v11, v25, v24
	v_fmac_f32_e32 v25, v26, v17
	v_fma_f32 v11, -v11, v25, v24
	v_div_fmas_f32 v11, v11, v17, v25
	v_div_fixup_f32 v12, v11, v16, v12
	v_add_f32_e32 v11, v6, v18
	v_mul_f32_e32 v11, 0xbfb8aa3b, v11
	v_pk_add_f32 v[80:81], v[80:81], v[12:13]
	v_exp_f32_e32 v12, v11
	v_add_f32_e32 v11, v7, v19
	v_mul_f32_e32 v11, 0xbfb8aa3b, v11
	v_exp_f32_e32 v13, v11
	s_nop 0
	v_pk_add_f32 v[12:13], v[12:13], 1.0 op_sel_hi:[1,0]
	s_nop 0
	v_div_scale_f32 v11, s[20:21], v13, v13, v15
	v_rcp_f32_e32 v16, v11
	s_nop 0
	v_fma_f32 v17, -v11, v16, 1.0
	v_fmac_f32_e32 v16, v17, v16
	v_div_scale_f32 v17, vcc, v15, v13, v15
	v_mul_f32_e32 v18, v17, v16
	v_fma_f32 v19, -v11, v18, v17
	v_fmac_f32_e32 v18, v19, v16
	v_fma_f32 v11, -v11, v18, v17
	v_div_fmas_f32 v11, v11, v16, v18
	v_div_fixup_f32 v13, v11, v13, v15
	v_div_scale_f32 v11, s[20:21], v12, v12, v14
	v_rcp_f32_e32 v15, v11
	s_nop 0
	v_fma_f32 v16, -v11, v15, 1.0
	v_fmac_f32_e32 v15, v16, v15
	v_div_scale_f32 v16, vcc, v14, v12, v14
	v_mul_f32_e32 v17, v16, v15
	v_fma_f32 v18, -v11, v17, v16
	v_fmac_f32_e32 v17, v18, v15
	v_fma_f32 v11, -v11, v17, v16
	v_div_fmas_f32 v11, v11, v15, v17
	v_div_fixup_f32 v12, v11, v12, v14
	v_add_f32_e32 v11, v0, v20
	v_mul_f32_e32 v11, 0xbfb8aa3b, v11
	v_exp_f32_e32 v16, v11
	v_add_f32_e32 v11, v1, v21
	v_mul_f32_e32 v11, 0xbfb8aa3b, v11
	v_pk_add_f32 v[76:77], v[76:77], v[12:13]
	v_exp_f32_e32 v17, v11
	ds_read_b128 v[12:15], v10 offset:50704
	v_pk_add_f32 v[16:17], v[16:17], 1.0 op_sel_hi:[1,0]
	s_waitcnt lgkmcnt(0)
	v_div_scale_f32 v11, s[20:21], v17, v17, v13
	v_rcp_f32_e32 v18, v11
	s_nop 0
	v_fma_f32 v19, -v11, v18, 1.0
	v_fmac_f32_e32 v18, v19, v18
	v_div_scale_f32 v19, vcc, v13, v17, v13
	v_mul_f32_e32 v20, v19, v18
	v_fma_f32 v21, -v11, v20, v19
	v_fmac_f32_e32 v20, v21, v18
	v_fma_f32 v11, -v11, v20, v19
	v_div_fmas_f32 v11, v11, v18, v20
	v_div_fixup_f32 v13, v11, v17, v13
	v_div_scale_f32 v11, s[20:21], v16, v16, v12
	v_rcp_f32_e32 v17, v11
	s_nop 0
	v_fma_f32 v18, -v11, v17, 1.0
	v_fmac_f32_e32 v17, v18, v17
	v_div_scale_f32 v18, vcc, v12, v16, v12
	v_mul_f32_e32 v19, v18, v17
	v_fma_f32 v20, -v11, v19, v18
	v_fmac_f32_e32 v19, v20, v17
	v_fma_f32 v11, -v11, v19, v18
	v_div_fmas_f32 v11, v11, v17, v19
	v_div_fixup_f32 v12, v11, v16, v12
	v_add_f32_e32 v11, v2, v22
	v_mul_f32_e32 v11, 0xbfb8aa3b, v11
	v_pk_add_f32 v[74:75], v[74:75], v[12:13]
	v_exp_f32_e32 v12, v11
	v_add_f32_e32 v11, v3, v23
	v_mul_f32_e32 v11, 0xbfb8aa3b, v11
	v_exp_f32_e32 v13, v11
	s_nop 0
	v_pk_add_f32 v[12:13], v[12:13], 1.0 op_sel_hi:[1,0]
	s_nop 0
	v_div_scale_f32 v11, s[20:21], v13, v13, v15
	v_rcp_f32_e32 v16, v11
	s_nop 0
	v_fma_f32 v17, -v11, v16, 1.0
	v_fmac_f32_e32 v16, v17, v16
	v_div_scale_f32 v17, vcc, v15, v13, v15
	v_mul_f32_e32 v18, v17, v16
	v_fma_f32 v19, -v11, v18, v17
	v_fmac_f32_e32 v18, v19, v16
	v_fma_f32 v11, -v11, v18, v17
	v_div_fmas_f32 v11, v11, v16, v18
	v_div_fixup_f32 v13, v11, v13, v15
	v_div_scale_f32 v11, s[20:21], v12, v12, v14
	v_rcp_f32_e32 v15, v11
	s_mov_b32 s20, 0xcd51000
	v_fma_f32 v16, -v11, v15, 1.0
	v_fmac_f32_e32 v15, v16, v15
	v_div_scale_f32 v16, vcc, v14, v12, v14
	v_mul_f32_e32 v17, v16, v15
	v_fma_f32 v18, -v11, v17, v16
	v_fmac_f32_e32 v17, v18, v15
	v_fma_f32 v11, -v11, v17, v16
	v_div_fmas_f32 v11, v11, v15, v17
	v_add_co_u32_e32 v8, vcc, s20, v8
	v_div_fixup_f32 v12, v11, v12, v14
	s_nop 0
	v_addc_co_u32_e32 v9, vcc, 0, v9, vcc
	v_pk_add_f32 v[70:71], v[70:71], v[12:13]
	s_waitcnt vmcnt(0)
	v_mov_b32_e32 v12, v56
	v_mov_b32_e32 v13, v57
	v_mov_b32_e32 v14, v58
	v_mov_b32_e32 v15, v59
	v_lshlrev_b32_e32 v11, 16, v12
	v_and_b32_e32 v12, 0xffff0000, v12
	v_add_f32_e32 v4, v4, v11
	v_add_f32_e32 v5, v5, v12
	v_mul_f32_e32 v4, 0xbfb8aa3b, v4
	v_mul_f32_e32 v5, 0xbfb8aa3b, v5
	v_lshlrev_b32_e32 v16, 16, v13
	v_and_b32_e32 v17, 0xffff0000, v13
	v_lshlrev_b32_e32 v18, 16, v14
	v_and_b32_e32 v19, 0xffff0000, v14
	v_lshlrev_b32_e32 v9, 16, v15
	v_and_b32_e32 v8, 0xffff0000, v15
	v_exp_f32_e32 v4, v4
	v_exp_f32_e32 v5, v5
	ds_read_b128 v[12:15], v10 offset:59136
	v_add_f32_e32 v0, v0, v18
	v_add_f32_e32 v1, v1, v19
	v_pk_add_f32 v[4:5], v[4:5], 1.0 op_sel_hi:[1,0]
	v_mul_f32_e32 v0, 0xbfb8aa3b, v0
	s_waitcnt lgkmcnt(0)
	v_div_scale_f32 v11, s[20:21], v5, v5, v13
	v_rcp_f32_e32 v20, v11
	v_mul_f32_e32 v1, 0xbfb8aa3b, v1
	v_exp_f32_e32 v0, v0
	v_exp_f32_e32 v1, v1
	v_fma_f32 v21, -v11, v20, 1.0
	v_fmac_f32_e32 v20, v21, v20
	v_div_scale_f32 v21, vcc, v13, v5, v13
	v_mul_f32_e32 v22, v21, v20
	v_fma_f32 v23, -v11, v22, v21
	v_fmac_f32_e32 v22, v23, v20
	v_fma_f32 v11, -v11, v22, v21
	v_div_fmas_f32 v11, v11, v20, v22
	v_div_fixup_f32 v5, v11, v5, v13
	v_div_scale_f32 v11, s[20:21], v4, v4, v12
	v_rcp_f32_e32 v13, v11
	v_pk_add_f32 v[0:1], v[0:1], 1.0 op_sel_hi:[1,0]
	v_fma_f32 v20, -v11, v13, 1.0
	v_fmac_f32_e32 v13, v20, v13
	v_div_scale_f32 v20, vcc, v12, v4, v12
	v_mul_f32_e32 v21, v20, v13
	v_fma_f32 v22, -v11, v21, v20
	v_fmac_f32_e32 v21, v22, v13
	v_fma_f32 v11, -v11, v21, v20
	v_div_fmas_f32 v11, v11, v13, v21
	v_div_fixup_f32 v4, v11, v4, v12
	v_pk_add_f32 v[72:73], v[72:73], v[4:5]
	v_add_f32_e32 v4, v6, v16
	v_add_f32_e32 v5, v7, v17
	v_mul_f32_e32 v4, 0xbfb8aa3b, v4
	v_mul_f32_e32 v5, 0xbfb8aa3b, v5
	v_exp_f32_e32 v4, v4
	v_exp_f32_e32 v5, v5
	s_nop 0
	v_pk_add_f32 v[4:5], v[4:5], 1.0 op_sel_hi:[1,0]
	s_nop 0
	v_div_scale_f32 v6, s[20:21], v5, v5, v15
	v_rcp_f32_e32 v7, v6
	s_nop 0
	v_fma_f32 v11, -v6, v7, 1.0
	v_fmac_f32_e32 v7, v11, v7
	v_div_scale_f32 v11, vcc, v15, v5, v15
	v_mul_f32_e32 v12, v11, v7
	v_fma_f32 v13, -v6, v12, v11
	v_fmac_f32_e32 v12, v13, v7
	v_fma_f32 v6, -v6, v12, v11
	v_div_fmas_f32 v6, v6, v7, v12
	v_div_fixup_f32 v5, v6, v5, v15
	v_div_scale_f32 v6, s[20:21], v4, v4, v14
	v_rcp_f32_e32 v7, v6
	s_nop 0
	v_fma_f32 v11, -v6, v7, 1.0
	v_fmac_f32_e32 v7, v11, v7
	v_div_scale_f32 v11, vcc, v14, v4, v14
	v_mul_f32_e32 v12, v11, v7
	v_fma_f32 v13, -v6, v12, v11
	v_fmac_f32_e32 v12, v13, v7
	v_fma_f32 v6, -v6, v12, v11
	v_div_fmas_f32 v6, v6, v7, v12
	v_div_fixup_f32 v4, v6, v4, v14
	v_pk_add_f32 v[68:69], v[68:69], v[4:5]
	ds_read_b128 v[4:7], v10 offset:59152
	s_waitcnt lgkmcnt(0)
	v_div_scale_f32 v10, s[20:21], v1, v1, v5
	v_rcp_f32_e32 v11, v10
	s_nop 0
	v_fma_f32 v12, -v10, v11, 1.0
	v_fmac_f32_e32 v11, v12, v11
	v_div_scale_f32 v12, vcc, v5, v1, v5
	v_mul_f32_e32 v13, v12, v11
	v_fma_f32 v14, -v10, v13, v12
	v_fmac_f32_e32 v13, v14, v11
	v_fma_f32 v10, -v10, v13, v12
	v_div_fmas_f32 v10, v10, v11, v13
	v_div_fixup_f32 v1, v10, v1, v5
	v_div_scale_f32 v5, s[20:21], v0, v0, v4
	v_rcp_f32_e32 v10, v5
	s_nop 0
	v_fma_f32 v11, -v5, v10, 1.0
	v_fmac_f32_e32 v10, v11, v10
	v_div_scale_f32 v11, vcc, v4, v0, v4
	v_mul_f32_e32 v12, v11, v10
	v_fma_f32 v13, -v5, v12, v11
	v_fmac_f32_e32 v12, v13, v10
	v_fma_f32 v5, -v5, v12, v11
	v_div_fmas_f32 v5, v5, v10, v12
	v_div_fixup_f32 v0, v5, v0, v4
	v_pk_add_f32 v[66:67], v[66:67], v[0:1]
	v_add_f32_e32 v0, v2, v9
	v_add_f32_e32 v1, v3, v8
	v_mul_f32_e32 v0, 0xbfb8aa3b, v0
	v_mul_f32_e32 v1, 0xbfb8aa3b, v1
	v_exp_f32_e32 v0, v0
	v_exp_f32_e32 v1, v1
	s_nop 0
	v_pk_add_f32 v[0:1], v[0:1], 1.0 op_sel_hi:[1,0]
	s_nop 0
	v_div_scale_f32 v2, s[20:21], v1, v1, v7
	v_rcp_f32_e32 v3, v2
	s_nop 0
	v_fma_f32 v4, -v2, v3, 1.0
	v_fmac_f32_e32 v3, v4, v3
	v_div_scale_f32 v4, vcc, v7, v1, v7
	v_mul_f32_e32 v5, v4, v3
	v_fma_f32 v8, -v2, v5, v4
	v_fmac_f32_e32 v5, v8, v3
	v_fma_f32 v2, -v2, v5, v4
	v_div_fmas_f32 v2, v2, v3, v5
	v_div_fixup_f32 v1, v2, v1, v7
	v_div_scale_f32 v2, s[20:21], v0, v0, v6
	v_rcp_f32_e32 v3, v2
	s_nop 0
	v_fma_f32 v4, -v2, v3, 1.0
	v_fmac_f32_e32 v3, v4, v3
	v_div_scale_f32 v4, vcc, v6, v0, v6
	v_mul_f32_e32 v5, v4, v3
	v_fma_f32 v7, -v2, v5, v4
	v_fmac_f32_e32 v5, v7, v3
	v_fma_f32 v2, -v2, v5, v4
	v_div_fmas_f32 v2, v2, v3, v5
	v_div_fixup_f32 v0, v2, v0, v6
	v_pk_add_f32 v[64:65], v[64:65], v[0:1]
	s_cbranch_scc0 .LBB0_137
	s_lshl_b64 s[4:5], s[4:5], 18
	v_readlane_b32 s6, v252, 21
	v_readlane_b32 s7, v252, 22
	s_add_u32 s4, s6, s4
	v_mov_b32_e32 v0, v211
	s_addc_u32 s5, s7, s5
	s_lshl_b32 s6, s14, 1
	s_add_u32 s4, s4, s6
	v_ashrrev_i32_e32 v4, 4, v0
	v_lshlrev_b32_e32 v0, 4, v0
	s_addc_u32 s5, s5, 0
	v_and_b32_e32 v208, 0xf0, v0
	v_ashrrev_i32_e32 v5, 31, v4
	v_lshl_add_u64 v[6:7], s[4:5], 0, v[208:209]
	v_lshlrev_b64 v[4:5], 11, v[4:5]
	v_lshl_add_u64 v[4:5], v[6:7], 0, v[4:5]
	s_mov_b32 s4, 0x8000
	v_cvt_pk_bf16_f32 v0, v126, v127
	v_cvt_pk_bf16_f32 v1, v124, v125
	v_cvt_pk_bf16_f32 v2, v120, v121
	v_cvt_pk_bf16_f32 v3, v104, v105
	v_add_co_u32_e32 v6, vcc, s4, v4
	global_store_dwordx4 v[4:5], v[0:3], off
	s_nop 0
	v_addc_co_u32_e32 v7, vcc, 0, v5, vcc
	v_cvt_pk_bf16_f32 v0, v122, v123
	v_cvt_pk_bf16_f32 v1, v118, v119
	v_cvt_pk_bf16_f32 v2, v114, v115
	v_cvt_pk_bf16_f32 v3, v110, v111
	s_mov_b32 s4, 0x10000
	global_store_dwordx4 v[6:7], v[0:3], off
	v_add_co_u32_e32 v6, vcc, s4, v4
	s_nop 0
	v_cvt_pk_bf16_f32 v0, v116, v117
	v_cvt_pk_bf16_f32 v1, v112, v113
	v_cvt_pk_bf16_f32 v2, v106, v107
	v_cvt_pk_bf16_f32 v3, v100, v101
	v_addc_co_u32_e32 v7, vcc, 0, v5, vcc
	s_mov_b32 s2, 0x18000
	global_store_dwordx4 v[6:7], v[0:3], off
	v_add_co_u32_e32 v6, vcc, s2, v4
	s_nop 0
	v_cvt_pk_bf16_f32 v0, v108, v109
	v_cvt_pk_bf16_f32 v1, v102, v103
	v_cvt_pk_bf16_f32 v2, v96, v97
	v_cvt_pk_bf16_f32 v3, v92, v93
	v_addc_co_u32_e32 v7, vcc, 0, v5, vcc
	s_mov_b32 s4, 0x20000
	global_store_dwordx4 v[6:7], v[0:3], off
	v_add_co_u32_e32 v6, vcc, s4, v4
	s_nop 0
	v_cvt_pk_bf16_f32 v0, v98, v99
	v_cvt_pk_bf16_f32 v1, v94, v95
	v_cvt_pk_bf16_f32 v2, v88, v89
	v_cvt_pk_bf16_f32 v3, v84, v85
	v_addc_co_u32_e32 v7, vcc, 0, v5, vcc
	s_mov_b32 s4, 0x28000
	global_store_dwordx4 v[6:7], v[0:3], off
	v_add_co_u32_e32 v6, vcc, s4, v4
	s_nop 0
	v_cvt_pk_bf16_f32 v0, v90, v91
	v_cvt_pk_bf16_f32 v1, v86, v87
	v_cvt_pk_bf16_f32 v2, v82, v83
	v_cvt_pk_bf16_f32 v3, v78, v79
	v_addc_co_u32_e32 v7, vcc, 0, v5, vcc
	s_mov_b32 s4, 0x30000
	global_store_dwordx4 v[6:7], v[0:3], off
	v_add_co_u32_e32 v6, vcc, s4, v4
	s_nop 0
	v_cvt_pk_bf16_f32 v0, v80, v81
	v_addc_co_u32_e32 v7, vcc, 0, v5, vcc
	v_cvt_pk_bf16_f32 v1, v76, v77
	v_cvt_pk_bf16_f32 v2, v74, v75
	v_cvt_pk_bf16_f32 v3, v70, v71
	v_add_co_u32_e32 v4, vcc, 0x38000, v4
	global_store_dwordx4 v[6:7], v[0:3], off
	s_nop 0
	v_addc_co_u32_e32 v5, vcc, 0, v5, vcc
	v_cvt_pk_bf16_f32 v0, v72, v73
	v_cvt_pk_bf16_f32 v1, v68, v69
	v_cvt_pk_bf16_f32 v2, v66, v67
	v_cvt_pk_bf16_f32 v3, v64, v65
	global_store_dwordx4 v[4:5], v[0:3], off
	s_barrier
	s_and_saveexec_b64 s[4:5], s[36:37]
	s_cbranch_execz .LBB0_131
	v_readlane_b32 s6, v253, 62
	s_nop 1
	v_mov_b32_e32 v0, s6
	ds_write_b32 v0, v144
	s_branch .LBB0_131
